# lru gates: weight/bias loads hoisted (up to 21 in flight) with re-derived waits
# speedup vs baseline: 1.0046x; 1.0046x over previous
; #define LAS __attribute__((address_space(3)))
; __device__ __forceinline__ unsigned pk2(float lo, float hi) { return pg8::cvt_pk_bf16(lo, hi); }
; template <bool FULL> __device__ __forceinline__ void lru_tile(const Args& a, int l, int tile, LAS unsigned char* lds, int tid, int lane, int wave) {
;     ...
;         u32x4 w; w.x = pk2(xc[0], xc[1]); w.y = pk2(xc[2], xc[3]); w.z = pk2(xc[4], xc[5]); w.w = pk2(xc[6], xc[7]);
;         *(LAS u32x4*)(lds + OFF_XC + (t * 264 + c8 * 8) * 2) = w;
;     }
;     __syncthreads();
;     {
;         const int cb = wave & 3, chh = wave >> 2; const bf16* WA = (const bf16*)(wl + WL_WA); const bf16* WX = (const bf16*)(wl + WL_WX);
;         const float* c8t = (const float*)(a.ws + WS_TAB) + (size_t)l * 256;
;         f32x4 av[8], bv[8];
; #pragma unroll
;         for (int et = 0; et < 8; ++et) {
;             const int e0 = chh * 128 + et * 16, nb = e0 >> 6, el = e0 & 63;
;             f32x4 ra = {0.f, 0.f, 0.f, 0.f}, ia = {0.f, 0.f, 0.f, 0.f};
; #pragma unroll
;             for (int ks = 0; ks < 2; ++ks) {
;                 const bf16x8 xv = *(const LAS bf16x8*)(lds + OFF_XC + ((cb * 16 + fr) * 264 + nb * 64 + 32 * ks + 8 * fq) * 2);
;                 const bf16x8 wa = *(const bf16x8*)(WA + (size_t)nb * 4096 + (el + fr) * 64 + 32 * ks + 8 * fq);
;                 const bf16x8 wx = *(const bf16x8*)(WX + (size_t)nb * 4096 + (el + fr) * 64 + 32 * ks + 8 * fq);
;                 MFMA16(wa, xv, ra); MFMA16(wx, xv, ia);
;             }
;             const int c0 = e0 + 4 * fq;
;             const f32x4 ba = *(const f32x4*)(a.in[22] + (size_t)l * 256 + c0), bx = *(const f32x4*)(a.in[24] + (size_t)l * 256 + c0), c8v = *(const f32x4*)(c8t + c0);
;             const u32x2 xr = *(const LAS u32x2*)(lds + OFF_XC + ((cb * 16 + fr) * 264 + c0) * 2);
;             float lav[4];
;             const float xcv[4] = {__uint_as_float(xr.x << 16), __uint_as_float(xr.x & 0xffff0000u), __uint_as_float(xr.y << 16), __uint_as_float(xr.y & 0xffff0000u)};
; #pragma unroll
;             for (int r = 0; r < 4; ++r) {
;                 const float rg = sigmoidf_(ra[r] + ba[r]), ig = sigmoidf_(ia[r] + bx[r]);
;                 const float la = c8v[r] * rg; const float av_ = __expf(la); const float m2 = -expm1f(2.0f * la);
;                 av[et][r] = av_; bv[et][r] = sqrtf(fmaxf(m2, 0.f)) * ig * xcv[r]; lav[r] = la;
.LBB0_1323:
	s_or_b64 exec, exec, s[0:1]
	s_waitcnt vmcnt(0)
	v_cvt_pk_bf16_f32 v4, v4, v5
	v_cvt_pk_bf16_f32 v5, v6, v7
	v_cvt_pk_bf16_f32 v6, v0, v1
	v_mad_u64_u32 v[0:1], s[0:1], v9, s12, v[8:9]
	s_ashr_i32 s4, s7, 8
	s_add_i32 s0, 0, 0x10000
	s_lshl_b32 s24, s4, 1
	v_lshl_add_u32 v0, v0, 1, s0
	s_bfe_u32 s1, s7, 0x20006
	s_ashr_i32 s25, s24, 31
	v_cvt_pk_bf16_f32 v7, v2, v3
	ds_write_b128 v0, v[4:7]
	v_lshrrev_b32_e32 v0, 4, v66
	s_lshl_b32 s5, s4, 7
	s_lshl_b32 s7, s1, 4
	s_lshl_b64 s[24:25], s[24:25], 13
	v_or_b32_e32 v79, s7, v77
	v_lshlrev_b32_e32 v1, 3, v0
	v_lshlrev_b32_e32 v86, 2, v0
	v_or_b32_e32 v0, s7, v67
	s_add_u32 s40, s57, s24
	v_mad_u32_u24 v50, v79, s12, v1
	v_ashrrev_i32_e32 v1, 31, v0
	s_addc_u32 s41, s58, s25
	v_lshlrev_b64 v[0:1], 11, v[0:1]
	v_lshlrev_b32_e32 v144, 7, v77
	s_add_u32 s42, s59, s24
	v_lshl_add_u64 v[52:53], s[78:79], 0, v[0:1]
	v_add_u32_e32 v2, s5, v50
	v_lshl_add_u64 v[0:1], s[40:41], 0, v[144:145]
	v_and_b32_e32 v68, 48, v66
	v_mov_b32_e32 v69, v145
	s_addc_u32 s43, s60, s25
	v_lshl_add_u64 v[20:21], v[0:1], 0, v[68:69]
	v_lshl_add_u64 v[0:1], s[42:43], 0, v[144:145]
	v_lshl_add_u32 v38, v2, 1, s0
	s_waitcnt lgkmcnt(0)
	s_barrier
	global_load_dwordx4 v[118:121], v[20:21], off
	global_load_dwordx4 v[122:125], v[20:21], off offset:64
	global_load_dwordx4 v[126:129], v[20:21], off offset:2048
	global_load_dwordx4 v[130:133], v[20:21], off offset:2112
	v_lshl_add_u64 v[22:23], v[0:1], 0, v[68:69]
	global_load_dwordx4 v[134:137], v[22:23], off
	global_load_dwordx4 v[138:141], v[22:23], off offset:64
	global_load_dwordx4 v[150:153], v[22:23], off offset:2048
	ds_read_b128 v[0:3], v38
	ds_read_b128 v[12:15], v38 offset:64
	v_or_b32_e32 v54, s5, v86
	v_ashrrev_i32_e32 v55, 31, v54
	v_readlane_b32 s28, v254, 47
	v_readlane_b32 s29, v254, 48
	v_readlane_b32 s16, v254, 45
	v_readlane_b32 s30, v254, 49
	v_readlane_b32 s17, v254, 46
	v_readlane_b32 s31, v254, 50
	v_mad_u32_u24 v24, v79, s12, v54
	v_lshl_add_u32 v51, v24, 1, s0
	v_lshl_add_u64 v[48:49], v[54:55], 1, v[52:53]
	v_or_b32_e32 v60, 0x1000, v144
	v_mov_b32_e32 v61, v145
	v_mov_b32_e32 v71, v145
	s_or_b32 s7, s5, 64
	s_ashr_i32 s24, s7, 6
	s_ashr_i32 s25, s24, 31
	s_lshl_b64 s[24:25], s[24:25], 13
	s_add_u32 s26, s57, s24
	s_addc_u32 s27, s58, s25
	s_add_u32 s24, s59, s24
	s_addc_u32 s25, s60, s25
	s_waitcnt vmcnt(6) lgkmcnt(1)
	v_mfma_f32_16x16x32_bf16 v[4:7], v[118:121], v[0:3], 0
	s_waitcnt vmcnt(2)
	v_mfma_f32_16x16x32_bf16 v[0:3], v[134:137], v[0:3], 0
	ds_read_b64 v[24:25], v51
	s_waitcnt vmcnt(2) lgkmcnt(1)
	v_mfma_f32_16x16x32_bf16 v[8:11], v[122:125], v[12:15], v[4:7]
	s_waitcnt vmcnt(1)
	v_mfma_f32_16x16x32_bf16 v[4:7], v[138:141], v[12:15], v[0:3]
	s_nop 2
	v_lshlrev_b64 v[0:1], 2, v[54:55]
	v_lshl_add_u64 v[40:41], s[28:29], 0, v[0:1]
	global_load_dwordx4 v[16:19], v[40:41], off
	v_lshl_add_u64 v[44:45], s[16:17], 0, v[0:1]
	v_lshl_add_u64 v[46:47], s[30:31], 0, v[0:1]
	global_load_dwordx4 v[0:3], v[44:45], off
	global_load_dwordx4 v[118:121], v[46:47], off
	s_waitcnt vmcnt(2)
	v_add_f32_e32 v8, v8, v16
	v_add_f32_e32 v9, v9, v17
	v_mul_f32_e32 v8, 0xbfb8aa3b, v8
	v_mul_f32_e32 v9, 0xbfb8aa3b, v9
	v_exp_f32_e32 v8, v8
	v_exp_f32_e32 v9, v9
	s_waitcnt vmcnt(0)
	v_add_f32_e32 v4, v4, v118
	v_add_f32_e32 v5, v5, v119
	v_add_f32_e32 v8, 1.0, v8
	v_add_f32_e32 v9, 1.0, v9
	v_rcp_f32_e32 v8, v8
	v_rcp_f32_e32 v9, v9
	s_waitcnt lgkmcnt(0)
	v_lshlrev_b32_e32 v12, 16, v24
	v_and_b32_e32 v13, 0xffff0000, v24
	v_add_f32_e32 v10, v10, v18
	v_pk_mul_f32 v[8:9], v[0:1], v[8:9]
	v_add_f32_e32 v11, v11, v19
	v_pk_add_f32 v[16:17], v[8:9], v[8:9]
	v_mul_f32_e32 v10, 0xbfb8aa3b, v10
	v_mul_f32_e32 v1, 0x3fb8aa3b, v16
	v_rndne_f32_e32 v1, v1
	v_fmamk_f32 v24, v1, 0xbf317218, v16
	v_fmac_f32_e32 v24, 0x3102e308, v1
	v_fmamk_f32 v26, v24, 0x395133b1, v177
	v_cmp_eq_f32_e32 vcc, s2, v1
	v_cvt_i32_f32_e32 v1, v1
	v_fmaak_f32 v26, v24, v26, 0x3c0887f9
	v_fmaak_f32 v26, v24, v26, 0x3d2aaa81
	v_fmaak_f32 v26, v24, v26, 0x3e2aaaab
	v_fma_f32 v26, v24, v26, 0.5
	v_ldexp_f32 v1, 1.0, v1
	v_mul_f32_e32 v26, v24, v26
	v_cndmask_b32_e32 v1, v1, v195, vcc
	v_fmac_f32_e32 v24, v24, v26
	v_add_f32_e32 v26, -1.0, v1
	v_fmac_f32_e32 v26, v1, v24
	v_add_f32_e32 v1, v26, v26
	v_cndmask_b32_e32 v1, v26, v1, vcc
	v_max_f32_e64 v1, -v1, 0
	v_cmp_gt_f32_e32 vcc, s19, v1
	v_mul_f32_e32 v24, 0x4f800000, v1
	v_mul_f32_e32 v11, 0xbfb8aa3b, v11
	v_cndmask_b32_e32 v1, v1, v24, vcc
	v_sqrt_f32_e32 v24, v1
	v_exp_f32_e32 v10, v10
	v_exp_f32_e32 v11, v11
	v_mul_f32_e32 v4, 0xbfb8aa3b, v4
	v_add_u32_e32 v26, -1, v24
	v_fma_f32 v27, -v26, v24, v1
	v_cmp_ge_f32_e64 s[36:37], 0, v27
	v_add_u32_e32 v27, 1, v24
	v_mul_f32_e32 v5, 0xbfb8aa3b, v5
	v_cndmask_b32_e64 v26, v24, v26, s[36:37]
	v_fma_f32 v24, -v27, v24, v1
	v_cmp_lt_f32_e64 s[36:37], 0, v24
	v_exp_f32_e32 v4, v4
	v_exp_f32_e32 v5, v5
	v_cndmask_b32_e64 v24, v26, v27, s[36:37]
	v_mul_f32_e32 v26, 0x37800000, v24
	v_cndmask_b32_e32 v24, v24, v26, vcc
	v_cmp_class_f32_e32 vcc, v1, v178
	v_add_f32_e32 v10, 1.0, v10
	v_add_f32_e32 v11, 1.0, v11
	v_cndmask_b32_e32 v1, v24, v1, vcc
	v_mul_f32_e32 v24, 0x3fb8aa3b, v17
	v_rndne_f32_e32 v24, v24
	v_fmamk_f32 v26, v24, 0xbf317218, v17
	v_fmac_f32_e32 v26, 0x3102e308, v24
	v_fmamk_f32 v27, v26, 0x395133b1, v177
	v_cmp_eq_f32_e32 vcc, s2, v24
	v_cvt_i32_f32_e32 v24, v24
	v_fmaak_f32 v27, v26, v27, 0x3c0887f9
	v_fmaak_f32 v27, v26, v27, 0x3d2aaa81
	v_fmaak_f32 v27, v26, v27, 0x3e2aaaab
	v_fma_f32 v27, v26, v27, 0.5
	v_ldexp_f32 v24, 1.0, v24
	v_mul_f32_e32 v27, v26, v27
	v_cndmask_b32_e32 v24, v24, v195, vcc
	v_fmac_f32_e32 v26, v26, v27
	v_add_f32_e32 v27, -1.0, v24
	v_fmac_f32_e32 v27, v24, v26
; #define LAS __attribute__((address_space(3)))
; __device__ __forceinline__ unsigned pk2(float lo, float hi) { return pg8::cvt_pk_bf16(lo, hi); }
; __device__ __forceinline__ float sigmoidf_(float x) { return __builtin_amdgcn_rcpf(1.0f + __expf(-x)); }
; #define MFMA16(X, Y, ACC) ACC = __builtin_amdgcn_mfma_f32_16x16x32_bf16(X, Y, ACC, 0, 0, 0)
; template <bool FULL> __device__ __forceinline__ void lru_tile(const Args& a, int l, int tile, LAS unsigned char* lds, int tid, int lane, int wave) {
;     ...
;             for (int ks = 0; ks < 2; ++ks) {
;                 const bf16x8 xv = *(const LAS bf16x8*)(lds + OFF_XC + ((cb * 16 + fr) * 264 + nb * 64 + 32 * ks + 8 * fq) * 2);
;                 const bf16x8 wa = *(const bf16x8*)(WA + (size_t)nb * 4096 + (el + fr) * 64 + 32 * ks + 8 * fq);
;                 const bf16x8 wx = *(const bf16x8*)(WX + (size_t)nb * 4096 + (el + fr) * 64 + 32 * ks + 8 * fq);
;                 MFMA16(wa, xv, ra); MFMA16(wx, xv, ia);
;             }
;             const int c0 = e0 + 4 * fq;
;             const f32x4 ba = *(const f32x4*)(a.in[22] + (size_t)l * 256 + c0), bx = *(const f32x4*)(a.in[24] + (size_t)l * 256 + c0), c8v = *(const f32x4*)(c8t + c0);
;             const u32x2 xr = *(const LAS u32x2*)(lds + OFF_XC + ((cb * 16 + fr) * 264 + c0) * 2);
;             float lav[4];
;             const float xcv[4] = {__uint_as_float(xr.x << 16), __uint_as_float(xr.x & 0xffff0000u), __uint_as_float(xr.y << 16), __uint_as_float(xr.y & 0xffff0000u)};
; #pragma unroll
;             for (int r = 0; r < 4; ++r) {
;                 const float rg = sigmoidf_(ra[r] + ba[r]), ig = sigmoidf_(ia[r] + bx[r]);
;                 const float la = c8v[r] * rg; const float av_ = __expf(la); const float m2 = -expm1f(2.0f * la);
;                 av[et][r] = av_; bv[et][r] = sqrtf(fmaxf(m2, 0.f)) * ig * xcv[r]; lav[r] = la;
;             }
;             {
;               bf16* yr = Y + (size_t)(t0 + cb * 16 + fr) * DM + c0;
;               u32x2 wl_; wl_.x = pk2(lav[0], lav[1]); wl_.y = pk2(lav[2], lav[3]); *(u32x2*)(yr + 768) = wl_;
;               u32x2 wb_; wb_.x = pk2(bv[et][0], bv[et][1]); wb_.y = pk2(bv[et][2], bv[et][3]); *(u32x2*)(yr + 512) = wb_; }
	v_add_f32_e32 v24, v27, v27
	v_cndmask_b32_e32 v24, v27, v24, vcc
	v_max_f32_e64 v24, -v24, 0
	v_cmp_gt_f32_e32 vcc, s19, v24
	v_mul_f32_e32 v26, 0x4f800000, v24
	v_rcp_f32_e32 v10, v10
	v_cndmask_b32_e32 v24, v24, v26, vcc
	v_sqrt_f32_e32 v26, v24
	v_rcp_f32_e32 v11, v11
	v_add_f32_e32 v4, 1.0, v4
	v_add_f32_e32 v5, 1.0, v5
	v_add_u32_e32 v27, -1, v26
	v_fma_f32 v28, -v27, v26, v24
	v_cmp_ge_f32_e64 s[36:37], 0, v28
	v_add_u32_e32 v28, 1, v26
	v_rcp_f32_e32 v4, v4
	v_cndmask_b32_e64 v27, v26, v27, s[36:37]
	v_fma_f32 v26, -v28, v26, v24
	v_cmp_lt_f32_e64 s[36:37], 0, v26
	v_rcp_f32_e32 v5, v5
	v_pk_mul_f32 v[10:11], v[2:3], v[10:11]
	v_cndmask_b32_e64 v26, v27, v28, s[36:37]
	global_load_dwordx4 v[28:31], v[22:23], off offset:2112
	v_mul_f32_e32 v27, 0x37800000, v26
	v_cndmask_b32_e32 v26, v26, v27, vcc
	v_cmp_class_f32_e32 vcc, v24, v178
	v_add_f32_e32 v6, v6, v120
	v_add_f32_e32 v7, v7, v121
	v_cndmask_b32_e32 v24, v26, v24, vcc
	v_cmp_nlt_f32_e32 vcc, s86, v16
	v_pk_add_f32 v[14:15], v[10:11], v[10:11]
	v_mul_f32_e32 v6, 0xbfb8aa3b, v6
	v_cndmask_b32_e32 v1, 0, v1, vcc
	v_cmp_nlt_f32_e32 vcc, s86, v17
	v_mul_f32_e32 v3, 0x3fb8aa3b, v14
	v_rndne_f32_e32 v3, v3
	v_cndmask_b32_e32 v24, 0, v24, vcc
	v_cmp_ngt_f32_e32 vcc, s56, v17
	v_mul_f32_e32 v7, 0xbfb8aa3b, v7
	v_exp_f32_e32 v6, v6
	v_cndmask_b32_e32 v17, 1.0, v24, vcc
	v_cmp_ngt_f32_e32 vcc, s56, v16
	v_exp_f32_e32 v7, v7
	v_add_f32_e32 v6, 1.0, v6
	v_cndmask_b32_e32 v16, 1.0, v1, vcc
	v_pk_mul_f32 v[4:5], v[4:5], v[16:17]
	v_fmamk_f32 v16, v3, 0xbf317218, v14
	v_fmac_f32_e32 v16, 0x3102e308, v3
	v_fmamk_f32 v17, v16, 0x395133b1, v177
	v_cmp_eq_f32_e32 vcc, s2, v3
	v_cvt_i32_f32_e32 v3, v3
	v_fmaak_f32 v17, v16, v17, 0x3c0887f9
	v_fmaak_f32 v17, v16, v17, 0x3d2aaa81
	v_fmaak_f32 v17, v16, v17, 0x3e2aaaab
	v_fma_f32 v17, v16, v17, 0.5
	v_ldexp_f32 v3, 1.0, v3
	v_mul_f32_e32 v17, v16, v17
	v_cndmask_b32_e32 v3, v3, v195, vcc
	v_fmac_f32_e32 v16, v16, v17
	v_add_f32_e32 v17, -1.0, v3
	v_fmac_f32_e32 v17, v3, v16
	v_add_f32_e32 v3, v17, v17
	v_cndmask_b32_e32 v3, v17, v3, vcc
	v_max_f32_e64 v3, -v3, 0
	v_cmp_gt_f32_e32 vcc, s19, v3
	v_mul_f32_e32 v16, 0x4f800000, v3
	v_add_f32_e32 v7, 1.0, v7
	v_cndmask_b32_e32 v3, v3, v16, vcc
	v_sqrt_f32_e32 v16, v3
	v_rcp_f32_e32 v6, v6
	v_rcp_f32_e32 v7, v7
	v_mul_f32_e32 v0, 0x3fb8aa3b, v8
	v_add_u32_e32 v17, -1, v16
	v_fma_f32 v18, -v17, v16, v3
	v_cmp_ge_f32_e64 s[36:37], 0, v18
	v_add_u32_e32 v18, 1, v16
	v_pk_mul_f32 v[4:5], v[4:5], v[12:13]
	v_cndmask_b32_e64 v17, v16, v17, s[36:37]
	v_fma_f32 v16, -v18, v16, v3
	v_cmp_lt_f32_e64 s[36:37], 0, v16
	v_mul_f32_e32 v1, 0x3fb8aa3b, v9
	v_lshlrev_b32_e32 v12, 16, v25
	v_cndmask_b32_e64 v16, v17, v18, s[36:37]
	v_mul_f32_e32 v17, 0x37800000, v16
	v_cndmask_b32_e32 v16, v16, v17, vcc
	v_cmp_class_f32_e32 vcc, v3, v178
	v_and_b32_e32 v13, 0xffff0000, v25
	v_cvt_pk_bf16_f32 v8, v8, v9
	v_cvt_pk_bf16_f32 v9, v10, v11
	global_store_dwordx2 v[48:49], v[8:9], off offset:1536
	v_cndmask_b32_e32 v3, v16, v3, vcc
	v_mul_f32_e32 v16, 0x3fb8aa3b, v15
	v_rndne_f32_e32 v16, v16
	v_fmamk_f32 v17, v16, 0xbf317218, v15
	v_fmac_f32_e32 v17, 0x3102e308, v16
	v_fmamk_f32 v18, v17, 0x395133b1, v177
	v_cmp_eq_f32_e32 vcc, s2, v16
	v_cvt_i32_f32_e32 v16, v16
	v_fmaak_f32 v18, v17, v18, 0x3c0887f9
	v_fmaak_f32 v18, v17, v18, 0x3d2aaa81
	v_fmaak_f32 v18, v17, v18, 0x3e2aaaab
	v_fma_f32 v18, v17, v18, 0.5
	v_ldexp_f32 v16, 1.0, v16
	v_mul_f32_e32 v18, v17, v18
	v_cndmask_b32_e32 v16, v16, v195, vcc
	v_fmac_f32_e32 v17, v17, v18
	v_add_f32_e32 v18, -1.0, v16
	v_fmac_f32_e32 v18, v16, v17
	v_add_f32_e32 v16, v18, v18
	v_cndmask_b32_e32 v16, v18, v16, vcc
	v_max_f32_e64 v16, -v16, 0
	v_cmp_gt_f32_e32 vcc, s19, v16
	v_mul_f32_e32 v17, 0x4f800000, v16
	v_cvt_pk_bf16_f32 v8, v4, v5
	v_mul_f32_e32 v2, 0x3fb8aa3b, v10
	v_cndmask_b32_e32 v16, v16, v17, vcc
	v_sqrt_f32_e32 v17, v16
	v_exp_f32_e32 v0, v0
	v_exp_f32_e32 v1, v1
	v_exp_f32_e32 v2, v2
	v_add_u32_e32 v18, -1, v17
	v_fma_f32 v19, -v18, v17, v16
	v_cmp_ge_f32_e64 s[36:37], 0, v19
	v_add_u32_e32 v19, 1, v17
	s_nop 0
	v_cndmask_b32_e64 v18, v17, v18, s[36:37]
	v_fma_f32 v17, -v19, v17, v16
	v_cmp_lt_f32_e64 s[36:37], 0, v17
	s_nop 1
	v_cndmask_b32_e64 v17, v18, v19, s[36:37]
	v_mul_f32_e32 v18, 0x37800000, v17
	v_cndmask_b32_e32 v17, v17, v18, vcc
	v_cmp_class_f32_e32 vcc, v16, v178
	s_nop 1
	v_cndmask_b32_e32 v16, v17, v16, vcc
	v_cmp_nlt_f32_e32 vcc, s86, v14
	s_nop 1
	v_cndmask_b32_e32 v3, 0, v3, vcc
	v_cmp_nlt_f32_e32 vcc, s86, v15
	s_nop 1
	v_cndmask_b32_e32 v16, 0, v16, vcc
	v_cmp_ngt_f32_e32 vcc, s56, v15
	s_nop 1
	v_cndmask_b32_e32 v15, 1.0, v16, vcc
	v_cmp_ngt_f32_e32 vcc, s56, v14
	s_nop 1
	v_cndmask_b32_e32 v14, 1.0, v3, vcc
	v_pk_mul_f32 v[6:7], v[6:7], v[14:15]
	v_mul_f32_e32 v3, 0x3fb8aa3b, v11
	v_pk_mul_f32 v[6:7], v[6:7], v[12:13]
	v_exp_f32_e32 v3, v3
	v_cvt_pk_bf16_f32 v9, v6, v7
	global_store_dwordx2 v[48:49], v[8:9], off offset:1024
	ds_read_b128 v[8:11], v38
	s_waitcnt vmcnt(0) lgkmcnt(0)
	v_mfma_f32_16x16x32_bf16 v[12:15], v[126:129], v[8:11], 0
	s_waitcnt vmcnt(0)
	v_mfma_f32_16x16x32_bf16 v[8:11], v[150:153], v[8:11], 0
	ds_read_b128 v[16:19], v38 offset:64
	s_waitcnt vmcnt(0) lgkmcnt(0)
	v_mfma_f32_16x16x32_bf16 v[20:23], v[130:133], v[16:19], v[12:15]
	s_waitcnt vmcnt(0)
	v_mfma_f32_16x16x32_bf16 v[12:15], v[28:31], v[16:19], v[8:11]
	global_load_dwordx4 v[24:27], v[40:41], off offset:64
	global_load_dwordx4 v[16:19], v[46:47], off offset:64
	s_nop 0
	global_load_dwordx4 v[8:11], v[44:45], off offset:64
	ds_read_b64 v[28:29], v51 offset:32
	s_waitcnt vmcnt(2)
	v_add_f32_e32 v20, v20, v24
	s_waitcnt vmcnt(1)
; __device__ __forceinline__ unsigned pk2(float lo, float hi) { return pg8::cvt_pk_bf16(lo, hi); }
; __device__ __forceinline__ float sigmoidf_(float x) { return __builtin_amdgcn_rcpf(1.0f + __expf(-x)); }
; template <bool FULL> __device__ __forceinline__ void lru_tile(const Args& a, int l, int tile, LAS unsigned char* lds, int tid, int lane, int wave) {
;     ...
;             const float xcv[4] = {__uint_as_float(xr.x << 16), __uint_as_float(xr.x & 0xffff0000u), __uint_as_float(xr.y << 16), __uint_as_float(xr.y & 0xffff0000u)};
; #pragma unroll
;             for (int r = 0; r < 4; ++r) {
;                 const float rg = sigmoidf_(ra[r] + ba[r]), ig = sigmoidf_(ia[r] + bx[r]);
;                 const float la = c8v[r] * rg; const float av_ = __expf(la); const float m2 = -expm1f(2.0f * la);
;                 av[et][r] = av_; bv[et][r] = sqrtf(fmaxf(m2, 0.f)) * ig * xcv[r]; lav[r] = la;
;             }
;             {
;               bf16* yr = Y + (size_t)(t0 + cb * 16 + fr) * DM + c0;
;               u32x2 wl_; wl_.x = pk2(lav[0], lav[1]); wl_.y = pk2(lav[2], lav[3]); *(u32x2*)(yr + 768) = wl_;
;               u32x2 wb_; wb_.x = pk2(bv[et][0], bv[et][1]); wb_.y = pk2(bv[et][2], bv[et][3]); *(u32x2*)(yr + 512) = wb_; }
	v_add_f32_e32 v12, v12, v16
	v_add_f32_e32 v16, v21, v25
	v_mul_f32_e32 v20, 0xbfb8aa3b, v20
	v_mul_f32_e32 v16, 0xbfb8aa3b, v16
	v_exp_f32_e32 v20, v20
	v_exp_f32_e32 v16, v16
	v_add_f32_e32 v13, v13, v17
	s_waitcnt lgkmcnt(0)
	v_lshlrev_b32_e32 v24, 16, v28
	v_add_f32_e32 v20, 1.0, v20
	v_add_f32_e32 v16, 1.0, v16
	v_rcp_f32_e32 v20, v20
	v_rcp_f32_e32 v21, v16
	v_and_b32_e32 v25, 0xffff0000, v28
	v_mul_f32_e32 v12, 0xbfb8aa3b, v12
	v_mul_f32_e32 v13, 0xbfb8aa3b, v13
	s_waitcnt vmcnt(0)
	v_pk_mul_f32 v[16:17], v[8:9], v[20:21]
	v_exp_f32_e32 v12, v12
	v_pk_add_f32 v[20:21], v[16:17], v[16:17]
	v_exp_f32_e32 v13, v13
	v_mul_f32_e32 v9, 0x3fb8aa3b, v20
	v_rndne_f32_e32 v9, v9
	v_fmamk_f32 v28, v9, 0xbf317218, v20
	v_fmac_f32_e32 v28, 0x3102e308, v9
	v_fmamk_f32 v30, v28, 0x395133b1, v177
	v_cmp_eq_f32_e32 vcc, s2, v9
	v_cvt_i32_f32_e32 v9, v9
	v_fmaak_f32 v30, v28, v30, 0x3c0887f9
	v_fmaak_f32 v30, v28, v30, 0x3d2aaa81
	v_fmaak_f32 v30, v28, v30, 0x3e2aaaab
	v_fma_f32 v30, v28, v30, 0.5
	v_ldexp_f32 v9, 1.0, v9
	v_mul_f32_e32 v30, v28, v30
	v_cndmask_b32_e32 v9, v9, v195, vcc
	v_fmac_f32_e32 v28, v28, v30
	v_add_f32_e32 v30, -1.0, v9
	v_fmac_f32_e32 v30, v9, v28
	v_add_f32_e32 v9, v30, v30
	v_cndmask_b32_e32 v9, v30, v9, vcc
	v_max_f32_e64 v9, -v9, 0
	v_cmp_gt_f32_e32 vcc, s19, v9
	v_mul_f32_e32 v28, 0x4f800000, v9
	v_add_f32_e32 v12, 1.0, v12
	v_cndmask_b32_e32 v9, v9, v28, vcc
	v_sqrt_f32_e32 v28, v9
	v_add_f32_e32 v13, 1.0, v13
	v_rcp_f32_e32 v12, v12
	v_rcp_f32_e32 v13, v13
	v_add_u32_e32 v30, -1, v28
	v_fma_f32 v31, -v30, v28, v9
	v_cmp_ge_f32_e64 s[36:37], 0, v31
	v_add_u32_e32 v31, 1, v28
	v_add_f32_e32 v14, v14, v18
	v_cndmask_b32_e64 v30, v28, v30, s[36:37]
	v_fma_f32 v28, -v31, v28, v9
	v_cmp_lt_f32_e64 s[36:37], 0, v28
	v_add_f32_e32 v18, v23, v27
	v_mul_f32_e32 v18, 0xbfb8aa3b, v18
	v_cndmask_b32_e64 v28, v30, v31, s[36:37]
	v_mul_f32_e32 v30, 0x37800000, v28
	v_cndmask_b32_e32 v28, v28, v30, vcc
	v_cmp_class_f32_e32 vcc, v9, v178
	v_exp_f32_e32 v18, v18
	v_add_f32_e32 v15, v15, v19
	v_cndmask_b32_e32 v9, v28, v9, vcc
	v_mul_f32_e32 v28, 0x3fb8aa3b, v21
	v_rndne_f32_e32 v28, v28
	v_fmamk_f32 v30, v28, 0xbf317218, v21
	v_fmac_f32_e32 v30, 0x3102e308, v28
	v_fmamk_f32 v31, v30, 0x395133b1, v177
	v_cmp_eq_f32_e32 vcc, s2, v28
	v_cvt_i32_f32_e32 v28, v28
	v_fmaak_f32 v31, v30, v31, 0x3c0887f9
	v_fmaak_f32 v31, v30, v31, 0x3d2aaa81
	v_fmaak_f32 v31, v30, v31, 0x3e2aaaab
	v_fma_f32 v31, v30, v31, 0.5
	v_ldexp_f32 v28, 1.0, v28
	v_mul_f32_e32 v31, v30, v31
	v_cndmask_b32_e32 v28, v28, v195, vcc
	v_fmac_f32_e32 v30, v30, v31
	v_add_f32_e32 v31, -1.0, v28
	v_fmac_f32_e32 v31, v28, v30
	v_add_f32_e32 v28, v31, v31
	v_cndmask_b32_e32 v28, v31, v28, vcc
	v_max_f32_e64 v28, -v28, 0
	v_cmp_gt_f32_e32 vcc, s19, v28
	v_mul_f32_e32 v30, 0x4f800000, v28
	v_add_f32_e32 v18, 1.0, v18
	v_cndmask_b32_e32 v28, v28, v30, vcc
	v_sqrt_f32_e32 v30, v28
	v_mul_f32_e32 v14, 0xbfb8aa3b, v14
	v_mul_f32_e32 v15, 0xbfb8aa3b, v15
	v_exp_f32_e32 v14, v14
	v_add_u32_e32 v31, -1, v30
	v_fma_f32 v32, -v31, v30, v28
	v_cmp_ge_f32_e64 s[36:37], 0, v32
	v_add_u32_e32 v32, 1, v30
	v_exp_f32_e32 v15, v15
	v_cndmask_b32_e64 v31, v30, v31, s[36:37]
	v_fma_f32 v30, -v32, v30, v28
	v_cmp_lt_f32_e64 s[36:37], 0, v30
	v_add_f32_e32 v14, 1.0, v14
	v_add_f32_e32 v15, 1.0, v15
	v_cndmask_b32_e64 v30, v31, v32, s[36:37]
	v_mul_f32_e32 v31, 0x37800000, v30
	v_cndmask_b32_e32 v30, v30, v31, vcc
	v_cmp_class_f32_e32 vcc, v28, v178
	v_rcp_f32_e32 v14, v14
	v_rcp_f32_e32 v15, v15
	v_cndmask_b32_e32 v28, v30, v28, vcc
	v_cmp_nlt_f32_e32 vcc, s86, v20
	v_mul_f32_e32 v8, 0x3fb8aa3b, v16
	v_and_b32_e32 v19, 0xffff0000, v29
	v_cndmask_b32_e32 v9, 0, v9, vcc
	v_cmp_nlt_f32_e32 vcc, s86, v21
	v_cvt_pk_bf16_f32 v16, v16, v17
	v_exp_f32_e32 v8, v8
	s_nop 0
	v_cndmask_b32_e32 v28, 0, v28, vcc
	v_cmp_ngt_f32_e32 vcc, s56, v21
	s_nop 1
	v_cndmask_b32_e32 v21, 1.0, v28, vcc
	v_cmp_ngt_f32_e32 vcc, s56, v20
	s_nop 1
	v_cndmask_b32_e32 v20, 1.0, v9, vcc
	v_pk_mul_f32 v[12:13], v[12:13], v[20:21]
	v_add_f32_e32 v20, v22, v26
	v_mul_f32_e32 v20, 0xbfb8aa3b, v20
	v_exp_f32_e32 v20, v20
	v_rcp_f32_e32 v21, v18
	v_pk_mul_f32 v[12:13], v[12:13], v[24:25]
	v_mul_f32_e32 v9, 0x3fb8aa3b, v17
	v_add_f32_e32 v20, 1.0, v20
	v_rcp_f32_e32 v20, v20
	v_lshlrev_b32_e32 v18, 16, v29
	v_exp_f32_e32 v9, v9
	v_pk_mul_f32 v[20:21], v[10:11], v[20:21]
	s_nop 0
	v_pk_add_f32 v[22:23], v[20:21], v[20:21]
	v_cvt_pk_bf16_f32 v17, v20, v21
	global_store_dwordx2 v[48:49], v[16:17], off offset:1568
	v_mul_f32_e32 v11, 0x3fb8aa3b, v22
	v_rndne_f32_e32 v11, v11
	v_fmamk_f32 v24, v11, 0xbf317218, v22
	v_fmac_f32_e32 v24, 0x3102e308, v11
	v_fmamk_f32 v25, v24, 0x395133b1, v177
	v_cmp_eq_f32_e32 vcc, s2, v11
	v_cvt_i32_f32_e32 v11, v11
	v_fmaak_f32 v25, v24, v25, 0x3c0887f9
	v_fmaak_f32 v25, v24, v25, 0x3d2aaa81
	v_fmaak_f32 v25, v24, v25, 0x3e2aaaab
	v_fma_f32 v25, v24, v25, 0.5
	v_ldexp_f32 v11, 1.0, v11
	v_mul_f32_e32 v25, v24, v25
	v_cndmask_b32_e32 v11, v11, v195, vcc
	v_fmac_f32_e32 v24, v24, v25
	v_add_f32_e32 v25, -1.0, v11
	v_fmac_f32_e32 v25, v11, v24
	v_add_f32_e32 v11, v25, v25
	v_cndmask_b32_e32 v11, v25, v11, vcc
	v_max_f32_e64 v11, -v11, 0
	v_cmp_gt_f32_e32 vcc, s19, v11
	v_mul_f32_e32 v24, 0x4f800000, v11
	v_cvt_pk_bf16_f32 v16, v12, v13
	v_mul_f32_e32 v10, 0x3fb8aa3b, v20
	v_cndmask_b32_e32 v11, v11, v24, vcc
	v_sqrt_f32_e32 v24, v11
	v_exp_f32_e32 v10, v10
	v_add_u32_e32 v25, -1, v24
	v_fma_f32 v26, -v25, v24, v11
	v_cmp_ge_f32_e64 s[36:37], 0, v26
	v_add_u32_e32 v26, 1, v24
	s_nop 0
	v_cndmask_b32_e64 v25, v24, v25, s[36:37]
	v_fma_f32 v24, -v26, v24, v11
	v_cmp_lt_f32_e64 s[36:37], 0, v24
	s_nop 1
; #define LAS __attribute__((address_space(3)))
; __device__ __forceinline__ unsigned pk2(float lo, float hi) { return pg8::cvt_pk_bf16(lo, hi); }
; __device__ __forceinline__ float sigmoidf_(float x) { return __builtin_amdgcn_rcpf(1.0f + __expf(-x)); }
; template <bool FULL> __device__ __forceinline__ void lru_tile(const Args& a, int l, int tile, LAS unsigned char* lds, int tid, int lane, int wave) {
;     ...
;         for (int et = 0; et < 8; ++et) {
;             const int e0 = chh * 128 + et * 16, nb = e0 >> 6, el = e0 & 63;
;             f32x4 ra = {0.f, 0.f, 0.f, 0.f}, ia = {0.f, 0.f, 0.f, 0.f};
; #pragma unroll
;             for (int ks = 0; ks < 2; ++ks) {
;                 const bf16x8 xv = *(const LAS bf16x8*)(lds + OFF_XC + ((cb * 16 + fr) * 264 + nb * 64 + 32 * ks + 8 * fq) * 2);
;                 const bf16x8 wa = *(const bf16x8*)(WA + (size_t)nb * 4096 + (el + fr) * 64 + 32 * ks + 8 * fq);
;                 const bf16x8 wx = *(const bf16x8*)(WX + (size_t)nb * 4096 + (el + fr) * 64 + 32 * ks + 8 * fq);
;                 MFMA16(wa, xv, ra); MFMA16(wx, xv, ia);
;             }
;             const int c0 = e0 + 4 * fq;
;             const f32x4 ba = *(const f32x4*)(a.in[22] + (size_t)l * 256 + c0), bx = *(const f32x4*)(a.in[24] + (size_t)l * 256 + c0), c8v = *(const f32x4*)(c8t + c0);
;             const u32x2 xr = *(const LAS u32x2*)(lds + OFF_XC + ((cb * 16 + fr) * 264 + c0) * 2);
;             float lav[4];
;             const float xcv[4] = {__uint_as_float(xr.x << 16), __uint_as_float(xr.x & 0xffff0000u), __uint_as_float(xr.y << 16), __uint_as_float(xr.y & 0xffff0000u)};
; #pragma unroll
;             for (int r = 0; r < 4; ++r) {
;                 const float rg = sigmoidf_(ra[r] + ba[r]), ig = sigmoidf_(ia[r] + bx[r]);
;                 const float la = c8v[r] * rg; const float av_ = __expf(la); const float m2 = -expm1f(2.0f * la);
;                 av[et][r] = av_; bv[et][r] = sqrtf(fmaxf(m2, 0.f)) * ig * xcv[r]; lav[r] = la;
;             }
;             {
;               bf16* yr = Y + (size_t)(t0 + cb * 16 + fr) * DM + c0;
;               u32x2 wl_; wl_.x = pk2(lav[0], lav[1]); wl_.y = pk2(lav[2], lav[3]); *(u32x2*)(yr + 768) = wl_;
;               u32x2 wb_; wb_.x = pk2(bv[et][0], bv[et][1]); wb_.y = pk2(bv[et][2], bv[et][3]); *(u32x2*)(yr + 512) = wb_; }
	v_cndmask_b32_e64 v24, v25, v26, s[36:37]
	v_mul_f32_e32 v25, 0x37800000, v24
	v_cndmask_b32_e32 v24, v24, v25, vcc
	v_cmp_class_f32_e32 vcc, v11, v178
	s_nop 1
	v_cndmask_b32_e32 v11, v24, v11, vcc
	v_mul_f32_e32 v24, 0x3fb8aa3b, v23
	v_rndne_f32_e32 v24, v24
	v_fmamk_f32 v25, v24, 0xbf317218, v23
	v_fmac_f32_e32 v25, 0x3102e308, v24
	v_fmamk_f32 v26, v25, 0x395133b1, v177
	v_cmp_eq_f32_e32 vcc, s2, v24
	v_cvt_i32_f32_e32 v24, v24
	v_fmaak_f32 v26, v25, v26, 0x3c0887f9
	v_fmaak_f32 v26, v25, v26, 0x3d2aaa81
	v_fmaak_f32 v26, v25, v26, 0x3e2aaaab
	v_fma_f32 v26, v25, v26, 0.5
	v_ldexp_f32 v24, 1.0, v24
	v_mul_f32_e32 v26, v25, v26
	v_cndmask_b32_e32 v24, v24, v195, vcc
	v_fmac_f32_e32 v25, v25, v26
	v_add_f32_e32 v26, -1.0, v24
	v_fmac_f32_e32 v26, v24, v25
	v_add_f32_e32 v24, v26, v26
	v_cndmask_b32_e32 v24, v26, v24, vcc
	v_max_f32_e64 v24, -v24, 0
	v_cmp_gt_f32_e32 vcc, s19, v24
	v_mul_f32_e32 v25, 0x4f800000, v24
	s_nop 0
	v_cndmask_b32_e32 v24, v24, v25, vcc
	v_sqrt_f32_e32 v25, v24
	s_nop 0
	v_add_u32_e32 v26, -1, v25
	v_fma_f32 v27, -v26, v25, v24
	v_cmp_ge_f32_e64 s[36:37], 0, v27
	v_add_u32_e32 v27, 1, v25
	s_nop 0
	v_cndmask_b32_e64 v26, v25, v26, s[36:37]
	v_fma_f32 v25, -v27, v25, v24
	v_cmp_lt_f32_e64 s[36:37], 0, v25
	s_nop 1
	v_cndmask_b32_e64 v25, v26, v27, s[36:37]
	v_mul_f32_e32 v26, 0x37800000, v25
	v_cndmask_b32_e32 v25, v25, v26, vcc
	v_cmp_class_f32_e32 vcc, v24, v178
	s_nop 1
	v_cndmask_b32_e32 v24, v25, v24, vcc
	v_cmp_nlt_f32_e32 vcc, s86, v22
	s_nop 1
	v_cndmask_b32_e32 v11, 0, v11, vcc
	v_cmp_nlt_f32_e32 vcc, s86, v23
	s_nop 1
	v_cndmask_b32_e32 v24, 0, v24, vcc
	v_cmp_ngt_f32_e32 vcc, s56, v23
	s_nop 1
	v_cndmask_b32_e32 v23, 1.0, v24, vcc
	v_cmp_ngt_f32_e32 vcc, s56, v22
	s_nop 1
	v_cndmask_b32_e32 v22, 1.0, v11, vcc
	v_pk_mul_f32 v[14:15], v[14:15], v[22:23]
	v_mul_f32_e32 v11, 0x3fb8aa3b, v21
	v_pk_mul_f32 v[14:15], v[14:15], v[18:19]
	v_exp_f32_e32 v11, v11
	v_cvt_pk_bf16_f32 v17, v14, v15
	global_store_dwordx2 v[48:49], v[16:17], off offset:1056
	v_lshl_add_u64 v[16:17], s[40:41], 0, v[60:61]
	v_lshl_add_u64 v[28:29], v[16:17], 0, v[68:69]
	global_load_dwordx4 v[118:121], v[28:29], off
	global_load_dwordx4 v[122:125], v[28:29], off offset:64
	v_lshl_add_u64 v[16:17], s[42:43], 0, v[60:61]
	v_lshl_add_u64 v[32:33], v[16:17], 0, v[68:69]
	global_load_dwordx4 v[126:129], v[32:33], off
	global_load_dwordx4 v[130:133], v[32:33], off offset:64
	ds_read_b128 v[16:19], v38
	s_waitcnt vmcnt(3) lgkmcnt(0)
	v_mfma_f32_16x16x32_bf16 v[20:23], v[118:121], v[16:19], 0
	s_waitcnt vmcnt(1)
	v_mfma_f32_16x16x32_bf16 v[16:19], v[126:129], v[16:19], 0
	ds_read_b128 v[24:27], v38 offset:64
	s_nop 0
	s_waitcnt vmcnt(1) lgkmcnt(0)
	v_mfma_f32_16x16x32_bf16 v[28:31], v[122:125], v[24:27], v[20:23]
	s_waitcnt vmcnt(0)
	v_mfma_f32_16x16x32_bf16 v[20:23], v[130:133], v[24:27], v[16:19]
	global_load_dwordx4 v[32:35], v[40:41], off offset:128
	global_load_dwordx4 v[24:27], v[46:47], off offset:128
	s_nop 0
	global_load_dwordx4 v[16:19], v[44:45], off offset:128
	ds_read_b64 v[36:37], v51 offset:64
	s_waitcnt vmcnt(2)
	v_add_f32_e32 v28, v28, v32
	s_waitcnt vmcnt(1)
	v_add_f32_e32 v20, v20, v24
	v_add_f32_e32 v24, v29, v33
	v_mul_f32_e32 v28, 0xbfb8aa3b, v28
	v_mul_f32_e32 v24, 0xbfb8aa3b, v24
	v_exp_f32_e32 v28, v28
	v_exp_f32_e32 v24, v24
	v_add_f32_e32 v21, v21, v25
	s_waitcnt lgkmcnt(0)
	v_lshlrev_b32_e32 v32, 16, v36
	v_add_f32_e32 v28, 1.0, v28
	v_add_f32_e32 v24, 1.0, v24
	v_rcp_f32_e32 v28, v28
	v_rcp_f32_e32 v29, v24
	v_and_b32_e32 v33, 0xffff0000, v36
	v_mul_f32_e32 v20, 0xbfb8aa3b, v20
	v_mul_f32_e32 v21, 0xbfb8aa3b, v21
	s_waitcnt vmcnt(0)
	v_pk_mul_f32 v[24:25], v[16:17], v[28:29]
	v_exp_f32_e32 v20, v20
	v_pk_add_f32 v[28:29], v[24:25], v[24:25]
	v_exp_f32_e32 v21, v21
	v_mul_f32_e32 v17, 0x3fb8aa3b, v28
	v_rndne_f32_e32 v17, v17
	v_fmamk_f32 v36, v17, 0xbf317218, v28
	v_fmac_f32_e32 v36, 0x3102e308, v17
	v_fmamk_f32 v39, v36, 0x395133b1, v177
	v_cmp_eq_f32_e32 vcc, s2, v17
	v_cvt_i32_f32_e32 v17, v17
	v_fmaak_f32 v39, v36, v39, 0x3c0887f9
	v_fmaak_f32 v39, v36, v39, 0x3d2aaa81
	v_fmaak_f32 v39, v36, v39, 0x3e2aaaab
	v_fma_f32 v39, v36, v39, 0.5
	v_ldexp_f32 v17, 1.0, v17
	v_mul_f32_e32 v39, v36, v39
	v_cndmask_b32_e32 v17, v17, v195, vcc
	v_fmac_f32_e32 v36, v36, v39
	v_add_f32_e32 v39, -1.0, v17
	v_fmac_f32_e32 v39, v17, v36
	v_add_f32_e32 v17, v39, v39
	v_cndmask_b32_e32 v17, v39, v17, vcc
	v_max_f32_e64 v17, -v17, 0
	v_cmp_gt_f32_e32 vcc, s19, v17
	v_mul_f32_e32 v36, 0x4f800000, v17
	v_add_f32_e32 v20, 1.0, v20
	v_cndmask_b32_e32 v17, v17, v36, vcc
	v_sqrt_f32_e32 v36, v17
	v_add_f32_e32 v21, 1.0, v21
	v_rcp_f32_e32 v20, v20
	v_rcp_f32_e32 v21, v21
	v_add_u32_e32 v39, -1, v36
	v_fma_f32 v42, -v39, v36, v17
	v_cmp_ge_f32_e64 s[36:37], 0, v42
	v_add_u32_e32 v42, 1, v36
	v_add_f32_e32 v22, v22, v26
	v_cndmask_b32_e64 v39, v36, v39, s[36:37]
	v_fma_f32 v36, -v42, v36, v17
	v_cmp_lt_f32_e64 s[36:37], 0, v36
	v_add_f32_e32 v26, v31, v35
	v_mul_f32_e32 v26, 0xbfb8aa3b, v26
	v_cndmask_b32_e64 v36, v39, v42, s[36:37]
	v_mul_f32_e32 v39, 0x37800000, v36
	v_cndmask_b32_e32 v36, v36, v39, vcc
	v_cmp_class_f32_e32 vcc, v17, v178
	v_exp_f32_e32 v26, v26
	v_add_f32_e32 v23, v23, v27
	v_cndmask_b32_e32 v17, v36, v17, vcc
	v_mul_f32_e32 v36, 0x3fb8aa3b, v29
	v_rndne_f32_e32 v36, v36
	v_fmamk_f32 v39, v36, 0xbf317218, v29
	v_fmac_f32_e32 v39, 0x3102e308, v36
	v_fmamk_f32 v42, v39, 0x395133b1, v177
	v_cmp_eq_f32_e32 vcc, s2, v36
	v_cvt_i32_f32_e32 v36, v36
	v_fmaak_f32 v42, v39, v42, 0x3c0887f9
	v_fmaak_f32 v42, v39, v42, 0x3d2aaa81
	v_fmaak_f32 v42, v39, v42, 0x3e2aaaab
	v_fma_f32 v42, v39, v42, 0.5
	v_ldexp_f32 v36, 1.0, v36
; #define LAS __attribute__((address_space(3)))
; __device__ __forceinline__ unsigned pk2(float lo, float hi) { return pg8::cvt_pk_bf16(lo, hi); }
; __device__ __forceinline__ float sigmoidf_(float x) { return __builtin_amdgcn_rcpf(1.0f + __expf(-x)); }
; #define MFMA16(X, Y, ACC) ACC = __builtin_amdgcn_mfma_f32_16x16x32_bf16(X, Y, ACC, 0, 0, 0)
; template <bool FULL> __device__ __forceinline__ void lru_tile(const Args& a, int l, int tile, LAS unsigned char* lds, int tid, int lane, int wave) {
;     ...
;             for (int ks = 0; ks < 2; ++ks) {
;                 const bf16x8 xv = *(const LAS bf16x8*)(lds + OFF_XC + ((cb * 16 + fr) * 264 + nb * 64 + 32 * ks + 8 * fq) * 2);
;                 const bf16x8 wa = *(const bf16x8*)(WA + (size_t)nb * 4096 + (el + fr) * 64 + 32 * ks + 8 * fq);
;                 const bf16x8 wx = *(const bf16x8*)(WX + (size_t)nb * 4096 + (el + fr) * 64 + 32 * ks + 8 * fq);
;                 MFMA16(wa, xv, ra); MFMA16(wx, xv, ia);
;     ...
;             const float xcv[4] = {__uint_as_float(xr.x << 16), __uint_as_float(xr.x & 0xffff0000u), __uint_as_float(xr.y << 16), __uint_as_float(xr.y & 0xffff0000u)};
; #pragma unroll
;             for (int r = 0; r < 4; ++r) {
;                 const float rg = sigmoidf_(ra[r] + ba[r]), ig = sigmoidf_(ia[r] + bx[r]);
;                 const float la = c8v[r] * rg; const float av_ = __expf(la); const float m2 = -expm1f(2.0f * la);
;                 av[et][r] = av_; bv[et][r] = sqrtf(fmaxf(m2, 0.f)) * ig * xcv[r]; lav[r] = la;
;             }
;             {
;               bf16* yr = Y + (size_t)(t0 + cb * 16 + fr) * DM + c0;
;               u32x2 wl_; wl_.x = pk2(lav[0], lav[1]); wl_.y = pk2(lav[2], lav[3]); *(u32x2*)(yr + 768) = wl_;
;               u32x2 wb_; wb_.x = pk2(bv[et][0], bv[et][1]); wb_.y = pk2(bv[et][2], bv[et][3]); *(u32x2*)(yr + 512) = wb_; }
	v_mul_f32_e32 v42, v39, v42
	v_cndmask_b32_e32 v36, v36, v195, vcc
	v_fmac_f32_e32 v39, v39, v42
	v_add_f32_e32 v42, -1.0, v36
	v_fmac_f32_e32 v42, v36, v39
	v_add_f32_e32 v36, v42, v42
	v_cndmask_b32_e32 v36, v42, v36, vcc
	v_max_f32_e64 v36, -v36, 0
	v_cmp_gt_f32_e32 vcc, s19, v36
	v_mul_f32_e32 v39, 0x4f800000, v36
	v_add_f32_e32 v26, 1.0, v26
	v_cndmask_b32_e32 v36, v36, v39, vcc
	v_sqrt_f32_e32 v39, v36
	v_mul_f32_e32 v22, 0xbfb8aa3b, v22
	v_mul_f32_e32 v23, 0xbfb8aa3b, v23
	v_exp_f32_e32 v22, v22
	v_add_u32_e32 v42, -1, v39
	v_fma_f32 v43, -v42, v39, v36
	v_cmp_ge_f32_e64 s[36:37], 0, v43
	v_add_u32_e32 v43, 1, v39
	v_exp_f32_e32 v23, v23
	v_cndmask_b32_e64 v42, v39, v42, s[36:37]
	v_fma_f32 v39, -v43, v39, v36
	v_cmp_lt_f32_e64 s[36:37], 0, v39
	v_add_f32_e32 v22, 1.0, v22
	v_add_f32_e32 v23, 1.0, v23
	v_cndmask_b32_e64 v39, v42, v43, s[36:37]
	v_mul_f32_e32 v42, 0x37800000, v39
	v_cndmask_b32_e32 v39, v39, v42, vcc
	v_cmp_class_f32_e32 vcc, v36, v178
	v_rcp_f32_e32 v22, v22
	v_rcp_f32_e32 v23, v23
	v_cndmask_b32_e32 v36, v39, v36, vcc
	v_cmp_nlt_f32_e32 vcc, s86, v28
	v_mul_f32_e32 v16, 0x3fb8aa3b, v24
	v_cvt_pk_bf16_f32 v24, v24, v25
	v_and_b32_e32 v27, 0xffff0000, v37
	v_cndmask_b32_e32 v17, 0, v17, vcc
	v_cmp_nlt_f32_e32 vcc, s86, v29
	v_exp_f32_e32 v16, v16
	s_nop 0
	v_cndmask_b32_e32 v36, 0, v36, vcc
	v_cmp_ngt_f32_e32 vcc, s56, v29
	s_nop 1
	v_cndmask_b32_e32 v29, 1.0, v36, vcc
	v_cmp_ngt_f32_e32 vcc, s56, v28
	s_nop 1
	v_cndmask_b32_e32 v28, 1.0, v17, vcc
	v_pk_mul_f32 v[20:21], v[20:21], v[28:29]
	v_add_f32_e32 v28, v30, v34
	v_mul_f32_e32 v28, 0xbfb8aa3b, v28
	v_exp_f32_e32 v28, v28
	v_rcp_f32_e32 v29, v26
	v_pk_mul_f32 v[20:21], v[20:21], v[32:33]
	v_mul_f32_e32 v17, 0x3fb8aa3b, v25
	v_add_f32_e32 v28, 1.0, v28
	v_rcp_f32_e32 v28, v28
	v_lshlrev_b32_e32 v26, 16, v37
	v_exp_f32_e32 v17, v17
	v_pk_mul_f32 v[28:29], v[18:19], v[28:29]
	s_nop 0
	v_pk_add_f32 v[30:31], v[28:29], v[28:29]
	v_cvt_pk_bf16_f32 v25, v28, v29
	global_store_dwordx2 v[48:49], v[24:25], off offset:1600
	v_mul_f32_e32 v19, 0x3fb8aa3b, v30
	v_rndne_f32_e32 v19, v19
	v_fmamk_f32 v32, v19, 0xbf317218, v30
	v_fmac_f32_e32 v32, 0x3102e308, v19
	v_fmamk_f32 v33, v32, 0x395133b1, v177
	v_cmp_eq_f32_e32 vcc, s2, v19
	v_cvt_i32_f32_e32 v19, v19
	v_fmaak_f32 v33, v32, v33, 0x3c0887f9
	v_fmaak_f32 v33, v32, v33, 0x3d2aaa81
	v_fmaak_f32 v33, v32, v33, 0x3e2aaaab
	v_fma_f32 v33, v32, v33, 0.5
	v_ldexp_f32 v19, 1.0, v19
	v_mul_f32_e32 v33, v32, v33
	v_cndmask_b32_e32 v19, v19, v195, vcc
	v_fmac_f32_e32 v32, v32, v33
	v_add_f32_e32 v33, -1.0, v19
	v_fmac_f32_e32 v33, v19, v32
	v_add_f32_e32 v19, v33, v33
	v_cndmask_b32_e32 v19, v33, v19, vcc
	v_max_f32_e64 v19, -v19, 0
	v_cmp_gt_f32_e32 vcc, s19, v19
	v_mul_f32_e32 v32, 0x4f800000, v19
	v_cvt_pk_bf16_f32 v24, v20, v21
	v_mul_f32_e32 v18, 0x3fb8aa3b, v28
	v_cndmask_b32_e32 v19, v19, v32, vcc
	v_sqrt_f32_e32 v32, v19
	v_exp_f32_e32 v18, v18
	v_add_u32_e32 v33, -1, v32
	v_fma_f32 v34, -v33, v32, v19
	v_cmp_ge_f32_e64 s[36:37], 0, v34
	v_add_u32_e32 v34, 1, v32
	s_nop 0
	v_cndmask_b32_e64 v33, v32, v33, s[36:37]
	v_fma_f32 v32, -v34, v32, v19
	v_cmp_lt_f32_e64 s[36:37], 0, v32
	s_nop 1
	v_cndmask_b32_e64 v32, v33, v34, s[36:37]
	v_mul_f32_e32 v33, 0x37800000, v32
	v_cndmask_b32_e32 v32, v32, v33, vcc
	v_cmp_class_f32_e32 vcc, v19, v178
	s_nop 1
	v_cndmask_b32_e32 v19, v32, v19, vcc
	v_mul_f32_e32 v32, 0x3fb8aa3b, v31
	v_rndne_f32_e32 v32, v32
	v_fmamk_f32 v33, v32, 0xbf317218, v31
	v_fmac_f32_e32 v33, 0x3102e308, v32
	v_fmamk_f32 v34, v33, 0x395133b1, v177
	v_cmp_eq_f32_e32 vcc, s2, v32
	v_cvt_i32_f32_e32 v32, v32
	v_fmaak_f32 v34, v33, v34, 0x3c0887f9
	v_fmaak_f32 v34, v33, v34, 0x3d2aaa81
	v_fmaak_f32 v34, v33, v34, 0x3e2aaaab
	v_fma_f32 v34, v33, v34, 0.5
	v_ldexp_f32 v32, 1.0, v32
	v_mul_f32_e32 v34, v33, v34
	v_cndmask_b32_e32 v32, v32, v195, vcc
	v_fmac_f32_e32 v33, v33, v34
	v_add_f32_e32 v34, -1.0, v32
	v_fmac_f32_e32 v34, v32, v33
	v_add_f32_e32 v32, v34, v34
	v_cndmask_b32_e32 v32, v34, v32, vcc
	v_max_f32_e64 v32, -v32, 0
	v_cmp_gt_f32_e32 vcc, s19, v32
	v_mul_f32_e32 v33, 0x4f800000, v32
	s_nop 0
	v_cndmask_b32_e32 v32, v32, v33, vcc
	v_sqrt_f32_e32 v33, v32
	s_nop 0
	v_add_u32_e32 v34, -1, v33
	v_fma_f32 v35, -v34, v33, v32
	v_cmp_ge_f32_e64 s[36:37], 0, v35
	v_add_u32_e32 v35, 1, v33
	s_nop 0
	v_cndmask_b32_e64 v34, v33, v34, s[36:37]
	v_fma_f32 v33, -v35, v33, v32
	v_cmp_lt_f32_e64 s[36:37], 0, v33
	s_nop 1
	v_cndmask_b32_e64 v33, v34, v35, s[36:37]
	v_mul_f32_e32 v34, 0x37800000, v33
	v_cndmask_b32_e32 v33, v33, v34, vcc
	v_cmp_class_f32_e32 vcc, v32, v178
	s_nop 1
	v_cndmask_b32_e32 v32, v33, v32, vcc
	v_cmp_nlt_f32_e32 vcc, s86, v30
	s_nop 1
	v_cndmask_b32_e32 v19, 0, v19, vcc
	v_cmp_nlt_f32_e32 vcc, s86, v31
	s_nop 1
	v_cndmask_b32_e32 v32, 0, v32, vcc
	v_cmp_ngt_f32_e32 vcc, s56, v31
	s_nop 1
	v_cndmask_b32_e32 v31, 1.0, v32, vcc
	v_cmp_ngt_f32_e32 vcc, s56, v30
	s_nop 1
	v_cndmask_b32_e32 v30, 1.0, v19, vcc
	v_pk_mul_f32 v[22:23], v[22:23], v[30:31]
	v_mul_f32_e32 v19, 0x3fb8aa3b, v29
	v_pk_mul_f32 v[22:23], v[22:23], v[26:27]
	v_exp_f32_e32 v19, v19
	v_cvt_pk_bf16_f32 v25, v22, v23
	global_store_dwordx2 v[48:49], v[24:25], off offset:1088
	v_mov_b32_e32 v24, 0x1800
	v_lshl_or_b32 v70, v66, 7, v24
	v_lshl_add_u64 v[24:25], s[40:41], 0, v[70:71]
	v_lshl_add_u64 v[36:37], v[24:25], 0, v[68:69]
	global_load_dwordx4 v[118:121], v[36:37], off
	global_load_dwordx4 v[122:125], v[36:37], off offset:64
	v_lshl_add_u64 v[24:25], s[42:43], 0, v[70:71]
	v_lshl_add_u64 v[42:43], v[24:25], 0, v[68:69]
	global_load_dwordx4 v[126:129], v[42:43], off
	global_load_dwordx4 v[56:59], v[42:43], off offset:64
	ds_read_b128 v[24:27], v38
	s_waitcnt vmcnt(3) lgkmcnt(0)
; #define LAS __attribute__((address_space(3)))
; __device__ __forceinline__ unsigned pk2(float lo, float hi) { return pg8::cvt_pk_bf16(lo, hi); }
; __device__ __forceinline__ float sigmoidf_(float x) { return __builtin_amdgcn_rcpf(1.0f + __expf(-x)); }
; #define MFMA16(X, Y, ACC) ACC = __builtin_amdgcn_mfma_f32_16x16x32_bf16(X, Y, ACC, 0, 0, 0)
; template <bool FULL> __device__ __forceinline__ void lru_tile(const Args& a, int l, int tile, LAS unsigned char* lds, int tid, int lane, int wave) {
;     ...
;             for (int ks = 0; ks < 2; ++ks) {
;                 const bf16x8 xv = *(const LAS bf16x8*)(lds + OFF_XC + ((cb * 16 + fr) * 264 + nb * 64 + 32 * ks + 8 * fq) * 2);
;                 const bf16x8 wa = *(const bf16x8*)(WA + (size_t)nb * 4096 + (el + fr) * 64 + 32 * ks + 8 * fq);
;                 const bf16x8 wx = *(const bf16x8*)(WX + (size_t)nb * 4096 + (el + fr) * 64 + 32 * ks + 8 * fq);
;                 MFMA16(wa, xv, ra); MFMA16(wx, xv, ia);
;             }
;             const int c0 = e0 + 4 * fq;
;             const f32x4 ba = *(const f32x4*)(a.in[22] + (size_t)l * 256 + c0), bx = *(const f32x4*)(a.in[24] + (size_t)l * 256 + c0), c8v = *(const f32x4*)(c8t + c0);
;             const u32x2 xr = *(const LAS u32x2*)(lds + OFF_XC + ((cb * 16 + fr) * 264 + c0) * 2);
;             float lav[4];
;             const float xcv[4] = {__uint_as_float(xr.x << 16), __uint_as_float(xr.x & 0xffff0000u), __uint_as_float(xr.y << 16), __uint_as_float(xr.y & 0xffff0000u)};
; #pragma unroll
;             for (int r = 0; r < 4; ++r) {
;                 const float rg = sigmoidf_(ra[r] + ba[r]), ig = sigmoidf_(ia[r] + bx[r]);
;                 const float la = c8v[r] * rg; const float av_ = __expf(la); const float m2 = -expm1f(2.0f * la);
;                 av[et][r] = av_; bv[et][r] = sqrtf(fmaxf(m2, 0.f)) * ig * xcv[r]; lav[r] = la;
;             }
;             {
;               bf16* yr = Y + (size_t)(t0 + cb * 16 + fr) * DM + c0;
;               u32x2 wl_; wl_.x = pk2(lav[0], lav[1]); wl_.y = pk2(lav[2], lav[3]); *(u32x2*)(yr + 768) = wl_;
;               u32x2 wb_; wb_.x = pk2(bv[et][0], bv[et][1]); wb_.y = pk2(bv[et][2], bv[et][3]); *(u32x2*)(yr + 512) = wb_; }
	v_mfma_f32_16x16x32_bf16 v[28:31], v[118:121], v[24:27], 0
	s_waitcnt vmcnt(1)
	v_mfma_f32_16x16x32_bf16 v[24:27], v[126:129], v[24:27], 0
	ds_read_b128 v[32:35], v38 offset:64
	s_nop 0
	global_load_dwordx4 v[40:43], v[40:41], off offset:192
	s_waitcnt vmcnt(2) lgkmcnt(0)
	v_mfma_f32_16x16x32_bf16 v[36:39], v[122:125], v[32:35], v[28:31]
	s_waitcnt vmcnt(1)
	v_mfma_f32_16x16x32_bf16 v[28:31], v[56:59], v[32:35], v[24:27]
	s_nop 0
	global_load_dwordx4 v[32:35], v[46:47], off offset:192
	global_load_dwordx4 v[24:27], v[44:45], off offset:192
	ds_read_b64 v[44:45], v51 offset:96
	v_or_b32_e32 v56, s7, v86
	v_mad_u32_u24 v56, v79, s12, v56
	v_lshl_add_u32 v56, v56, 1, s0
	s_waitcnt vmcnt(2)
	v_add_f32_e32 v36, v36, v40
	s_waitcnt vmcnt(1)
	v_add_f32_e32 v28, v28, v32
	v_add_f32_e32 v32, v37, v41
	v_mul_f32_e32 v36, 0xbfb8aa3b, v36
	v_mul_f32_e32 v32, 0xbfb8aa3b, v32
	v_exp_f32_e32 v36, v36
	v_exp_f32_e32 v32, v32
	v_add_f32_e32 v29, v29, v33
	s_waitcnt lgkmcnt(0)
	v_lshlrev_b32_e32 v40, 16, v44
	v_add_f32_e32 v36, 1.0, v36
	v_add_f32_e32 v32, 1.0, v32
	v_rcp_f32_e32 v36, v36
	v_rcp_f32_e32 v37, v32
	v_and_b32_e32 v41, 0xffff0000, v44
	v_mul_f32_e32 v28, 0xbfb8aa3b, v28
	v_mul_f32_e32 v29, 0xbfb8aa3b, v29
	s_waitcnt vmcnt(0)
	v_pk_mul_f32 v[32:33], v[24:25], v[36:37]
	v_exp_f32_e32 v28, v28
	v_pk_add_f32 v[36:37], v[32:33], v[32:33]
	v_exp_f32_e32 v29, v29
	v_mul_f32_e32 v25, 0x3fb8aa3b, v36
	v_rndne_f32_e32 v25, v25
	v_fmamk_f32 v44, v25, 0xbf317218, v36
	v_fmac_f32_e32 v44, 0x3102e308, v25
	v_fmamk_f32 v46, v44, 0x395133b1, v177
	v_cmp_eq_f32_e32 vcc, s2, v25
	v_cvt_i32_f32_e32 v25, v25
	v_fmaak_f32 v46, v44, v46, 0x3c0887f9
	v_fmaak_f32 v46, v44, v46, 0x3d2aaa81
	v_fmaak_f32 v46, v44, v46, 0x3e2aaaab
	v_fma_f32 v46, v44, v46, 0.5
	v_ldexp_f32 v25, 1.0, v25
	v_mul_f32_e32 v46, v44, v46
	v_cndmask_b32_e32 v25, v25, v195, vcc
	v_fmac_f32_e32 v44, v44, v46
	v_add_f32_e32 v46, -1.0, v25
	v_fmac_f32_e32 v46, v25, v44
	v_add_f32_e32 v25, v46, v46
	v_cndmask_b32_e32 v25, v46, v25, vcc
	v_max_f32_e64 v25, -v25, 0
	v_cmp_gt_f32_e32 vcc, s19, v25
	v_mul_f32_e32 v44, 0x4f800000, v25
	v_add_f32_e32 v28, 1.0, v28
	v_cndmask_b32_e32 v25, v25, v44, vcc
	v_sqrt_f32_e32 v44, v25
	v_add_f32_e32 v29, 1.0, v29
	v_rcp_f32_e32 v28, v28
	v_rcp_f32_e32 v29, v29
	v_add_u32_e32 v46, -1, v44
	v_fma_f32 v47, -v46, v44, v25
	v_cmp_ge_f32_e64 s[36:37], 0, v47
	v_add_u32_e32 v47, 1, v44
	v_add_f32_e32 v30, v30, v34
	v_cndmask_b32_e64 v46, v44, v46, s[36:37]
	v_fma_f32 v44, -v47, v44, v25
	v_cmp_lt_f32_e64 s[36:37], 0, v44
	v_add_f32_e32 v34, v39, v43
	v_mul_f32_e32 v34, 0xbfb8aa3b, v34
	v_cndmask_b32_e64 v44, v46, v47, s[36:37]
	v_mul_f32_e32 v46, 0x37800000, v44
	v_cndmask_b32_e32 v44, v44, v46, vcc
	v_cmp_class_f32_e32 vcc, v25, v178
	v_exp_f32_e32 v34, v34
	v_add_f32_e32 v31, v31, v35
	v_cndmask_b32_e32 v25, v44, v25, vcc
	v_mul_f32_e32 v44, 0x3fb8aa3b, v37
	v_rndne_f32_e32 v44, v44
	v_fmamk_f32 v46, v44, 0xbf317218, v37
	v_fmac_f32_e32 v46, 0x3102e308, v44
	v_fmamk_f32 v47, v46, 0x395133b1, v177
	v_cmp_eq_f32_e32 vcc, s2, v44
	v_cvt_i32_f32_e32 v44, v44
	v_fmaak_f32 v47, v46, v47, 0x3c0887f9
	v_fmaak_f32 v47, v46, v47, 0x3d2aaa81
	v_fmaak_f32 v47, v46, v47, 0x3e2aaaab
	v_fma_f32 v47, v46, v47, 0.5
	v_ldexp_f32 v44, 1.0, v44
	v_mul_f32_e32 v47, v46, v47
	v_cndmask_b32_e32 v44, v44, v195, vcc
	v_fmac_f32_e32 v46, v46, v47
	v_add_f32_e32 v47, -1.0, v44
	v_fmac_f32_e32 v47, v44, v46
	v_add_f32_e32 v44, v47, v47
	v_cndmask_b32_e32 v44, v47, v44, vcc
	v_max_f32_e64 v44, -v44, 0
	v_cmp_gt_f32_e32 vcc, s19, v44
	v_mul_f32_e32 v46, 0x4f800000, v44
	v_add_f32_e32 v34, 1.0, v34
	v_cndmask_b32_e32 v44, v44, v46, vcc
	v_sqrt_f32_e32 v46, v44
	v_mul_f32_e32 v30, 0xbfb8aa3b, v30
	v_mul_f32_e32 v31, 0xbfb8aa3b, v31
	v_exp_f32_e32 v30, v30
	v_add_u32_e32 v47, -1, v46
	v_fma_f32 v51, -v47, v46, v44
	v_cmp_ge_f32_e64 s[36:37], 0, v51
	v_add_u32_e32 v51, 1, v46
	v_exp_f32_e32 v31, v31
	v_cndmask_b32_e64 v47, v46, v47, s[36:37]
	v_fma_f32 v46, -v51, v46, v44
	v_cmp_lt_f32_e64 s[36:37], 0, v46
	v_add_f32_e32 v30, 1.0, v30
	v_add_f32_e32 v31, 1.0, v31
	v_cndmask_b32_e64 v46, v47, v51, s[36:37]
	v_mul_f32_e32 v47, 0x37800000, v46
	v_cndmask_b32_e32 v46, v46, v47, vcc
	v_cmp_class_f32_e32 vcc, v44, v178
	v_rcp_f32_e32 v30, v30
	v_rcp_f32_e32 v31, v31
	v_cndmask_b32_e32 v44, v46, v44, vcc
	v_cmp_nlt_f32_e32 vcc, s86, v36
	v_mul_f32_e32 v24, 0x3fb8aa3b, v32
	v_and_b32_e32 v35, 0xffff0000, v45
	v_cndmask_b32_e32 v25, 0, v25, vcc
	v_cmp_nlt_f32_e32 vcc, s86, v37
	v_cvt_pk_bf16_f32 v32, v32, v33
	v_exp_f32_e32 v24, v24
	s_nop 0
	v_cndmask_b32_e32 v44, 0, v44, vcc
	v_cmp_ngt_f32_e32 vcc, s56, v37
	s_nop 1
	v_cndmask_b32_e32 v37, 1.0, v44, vcc
	v_cmp_ngt_f32_e32 vcc, s56, v36
	s_nop 1
	v_cndmask_b32_e32 v36, 1.0, v25, vcc
	v_pk_mul_f32 v[28:29], v[28:29], v[36:37]
	v_add_f32_e32 v36, v38, v42
	v_mul_f32_e32 v36, 0xbfb8aa3b, v36
	v_exp_f32_e32 v36, v36
	v_rcp_f32_e32 v37, v34
	v_pk_mul_f32 v[28:29], v[28:29], v[40:41]
	v_mul_f32_e32 v25, 0x3fb8aa3b, v33
	v_add_f32_e32 v36, 1.0, v36
	v_rcp_f32_e32 v36, v36
	v_lshlrev_b32_e32 v34, 16, v45
	v_exp_f32_e32 v25, v25
	v_pk_mul_f32 v[36:37], v[26:27], v[36:37]
	s_nop 0
	v_pk_add_f32 v[38:39], v[36:37], v[36:37]
	v_cvt_pk_bf16_f32 v33, v36, v37
	global_store_dwordx2 v[48:49], v[32:33], off offset:1632
	v_mul_f32_e32 v27, 0x3fb8aa3b, v38
	v_rndne_f32_e32 v27, v27
	v_fmamk_f32 v40, v27, 0xbf317218, v38
	v_fmac_f32_e32 v40, 0x3102e308, v27
	v_fmamk_f32 v41, v40, 0x395133b1, v177
	v_cmp_eq_f32_e32 vcc, s2, v27
	v_cvt_i32_f32_e32 v27, v27
	v_fmaak_f32 v41, v40, v41, 0x3c0887f9
	v_fmaak_f32 v41, v40, v41, 0x3d2aaa81
	v_fmaak_f32 v41, v40, v41, 0x3e2aaaab
; #define LAS __attribute__((address_space(3)))
; __device__ __forceinline__ unsigned pk2(float lo, float hi) { return pg8::cvt_pk_bf16(lo, hi); }
; __device__ __forceinline__ float sigmoidf_(float x) { return __builtin_amdgcn_rcpf(1.0f + __expf(-x)); }
; #define MFMA16(X, Y, ACC) ACC = __builtin_amdgcn_mfma_f32_16x16x32_bf16(X, Y, ACC, 0, 0, 0)
; template <bool FULL> __device__ __forceinline__ void lru_tile(const Args& a, int l, int tile, LAS unsigned char* lds, int tid, int lane, int wave) {
;     ...
;             for (int ks = 0; ks < 2; ++ks) {
;                 const bf16x8 xv = *(const LAS bf16x8*)(lds + OFF_XC + ((cb * 16 + fr) * 264 + nb * 64 + 32 * ks + 8 * fq) * 2);
;                 const bf16x8 wa = *(const bf16x8*)(WA + (size_t)nb * 4096 + (el + fr) * 64 + 32 * ks + 8 * fq);
;                 const bf16x8 wx = *(const bf16x8*)(WX + (size_t)nb * 4096 + (el + fr) * 64 + 32 * ks + 8 * fq);
;                 MFMA16(wa, xv, ra); MFMA16(wx, xv, ia);
;     ...
;             for (int r = 0; r < 4; ++r) {
;                 const float rg = sigmoidf_(ra[r] + ba[r]), ig = sigmoidf_(ia[r] + bx[r]);
;                 const float la = c8v[r] * rg; const float av_ = __expf(la); const float m2 = -expm1f(2.0f * la);
;                 av[et][r] = av_; bv[et][r] = sqrtf(fmaxf(m2, 0.f)) * ig * xcv[r]; lav[r] = la;
;             }
;             {
;               bf16* yr = Y + (size_t)(t0 + cb * 16 + fr) * DM + c0;
;               u32x2 wl_; wl_.x = pk2(lav[0], lav[1]); wl_.y = pk2(lav[2], lav[3]); *(u32x2*)(yr + 768) = wl_;
;               u32x2 wb_; wb_.x = pk2(bv[et][0], bv[et][1]); wb_.y = pk2(bv[et][2], bv[et][3]); *(u32x2*)(yr + 512) = wb_; }
	v_fma_f32 v41, v40, v41, 0.5
	v_ldexp_f32 v27, 1.0, v27
	v_mul_f32_e32 v41, v40, v41
	v_cndmask_b32_e32 v27, v27, v195, vcc
	v_fmac_f32_e32 v40, v40, v41
	v_add_f32_e32 v41, -1.0, v27
	v_fmac_f32_e32 v41, v27, v40
	v_add_f32_e32 v27, v41, v41
	v_cndmask_b32_e32 v27, v41, v27, vcc
	v_max_f32_e64 v27, -v27, 0
	v_cmp_gt_f32_e32 vcc, s19, v27
	v_mul_f32_e32 v40, 0x4f800000, v27
	v_cvt_pk_bf16_f32 v32, v28, v29
	v_mul_f32_e32 v26, 0x3fb8aa3b, v36
	v_cndmask_b32_e32 v27, v27, v40, vcc
	v_sqrt_f32_e32 v40, v27
	v_exp_f32_e32 v26, v26
	v_add_u32_e32 v41, -1, v40
	v_fma_f32 v42, -v41, v40, v27
	v_cmp_ge_f32_e64 s[36:37], 0, v42
	v_add_u32_e32 v42, 1, v40
	s_nop 0
	v_cndmask_b32_e64 v41, v40, v41, s[36:37]
	v_fma_f32 v40, -v42, v40, v27
	v_cmp_lt_f32_e64 s[36:37], 0, v40
	s_nop 1
	v_cndmask_b32_e64 v40, v41, v42, s[36:37]
	v_mul_f32_e32 v41, 0x37800000, v40
	v_cndmask_b32_e32 v40, v40, v41, vcc
	v_cmp_class_f32_e32 vcc, v27, v178
	s_nop 1
	v_cndmask_b32_e32 v27, v40, v27, vcc
	v_mul_f32_e32 v40, 0x3fb8aa3b, v39
	v_rndne_f32_e32 v40, v40
	v_fmamk_f32 v41, v40, 0xbf317218, v39
	v_fmac_f32_e32 v41, 0x3102e308, v40
	v_fmamk_f32 v42, v41, 0x395133b1, v177
	v_cmp_eq_f32_e32 vcc, s2, v40
	v_cvt_i32_f32_e32 v40, v40
	v_fmaak_f32 v42, v41, v42, 0x3c0887f9
	v_fmaak_f32 v42, v41, v42, 0x3d2aaa81
	v_fmaak_f32 v42, v41, v42, 0x3e2aaaab
	v_fma_f32 v42, v41, v42, 0.5
	v_ldexp_f32 v40, 1.0, v40
	v_mul_f32_e32 v42, v41, v42
	v_cndmask_b32_e32 v40, v40, v195, vcc
	v_fmac_f32_e32 v41, v41, v42
	v_add_f32_e32 v42, -1.0, v40
	v_fmac_f32_e32 v42, v40, v41
	v_add_f32_e32 v40, v42, v42
	v_cndmask_b32_e32 v40, v42, v40, vcc
	v_max_f32_e64 v40, -v40, 0
	v_cmp_gt_f32_e32 vcc, s19, v40
	v_mul_f32_e32 v41, 0x4f800000, v40
	s_nop 0
	v_cndmask_b32_e32 v40, v40, v41, vcc
	v_sqrt_f32_e32 v41, v40
	s_nop 0
	v_add_u32_e32 v42, -1, v41
	v_fma_f32 v43, -v42, v41, v40
	v_cmp_ge_f32_e64 s[36:37], 0, v43
	v_add_u32_e32 v43, 1, v41
	s_nop 0
	v_cndmask_b32_e64 v42, v41, v42, s[36:37]
	v_fma_f32 v41, -v43, v41, v40
	v_cmp_lt_f32_e64 s[36:37], 0, v41
	s_nop 1
	v_cndmask_b32_e64 v41, v42, v43, s[36:37]
	v_mul_f32_e32 v42, 0x37800000, v41
	v_cndmask_b32_e32 v41, v41, v42, vcc
	v_cmp_class_f32_e32 vcc, v40, v178
	s_nop 1
	v_cndmask_b32_e32 v40, v41, v40, vcc
	v_cmp_nlt_f32_e32 vcc, s86, v38
	s_nop 1
	v_cndmask_b32_e32 v27, 0, v27, vcc
	v_cmp_nlt_f32_e32 vcc, s86, v39
	s_nop 1
	v_cndmask_b32_e32 v40, 0, v40, vcc
	v_cmp_ngt_f32_e32 vcc, s56, v39
	s_nop 1
	v_cndmask_b32_e32 v39, 1.0, v40, vcc
	v_cmp_ngt_f32_e32 vcc, s56, v38
	s_nop 1
	v_cndmask_b32_e32 v38, 1.0, v27, vcc
	v_pk_mul_f32 v[30:31], v[30:31], v[38:39]
	v_mul_f32_e32 v27, 0x3fb8aa3b, v37
	v_pk_mul_f32 v[30:31], v[30:31], v[34:35]
	v_add_u32_e32 v34, s7, v50
	v_cvt_pk_bf16_f32 v33, v30, v31
	global_store_dwordx2 v[48:49], v[32:33], off offset:1120
	v_lshl_add_u64 v[32:33], s[26:27], 0, v[144:145]
	v_lshl_add_u64 v[48:49], v[32:33], 0, v[68:69]
	global_load_dwordx4 v[118:121], v[48:49], off
	global_load_dwordx4 v[122:125], v[48:49], off offset:64
	v_lshl_add_u64 v[32:33], s[24:25], 0, v[144:145]
	v_lshl_add_u32 v87, v34, 1, s0
	v_lshl_add_u64 v[50:51], v[32:33], 0, v[68:69]
	global_load_dwordx4 v[126:129], v[50:51], off
	global_load_dwordx4 v[130:133], v[50:51], off offset:64
	ds_read_b128 v[32:35], v87
	s_waitcnt vmcnt(3) lgkmcnt(0)
	v_mfma_f32_16x16x32_bf16 v[36:39], v[118:121], v[32:35], 0
	ds_read_b128 v[44:47], v87 offset:64
	s_ashr_i32 s7, s5, 31
	v_mov_b32_e32 v55, s7
	s_waitcnt vmcnt(1)
	v_mfma_f32_16x16x32_bf16 v[32:35], v[126:129], v[32:35], 0
	s_nop 0
	ds_read_b64 v[56:57], v56
	s_or_b32 s7, s5, 0x50
	s_waitcnt vmcnt(1) lgkmcnt(1)
	v_mfma_f32_16x16x32_bf16 v[40:43], v[122:125], v[44:47], v[36:39]
	s_nop 2
	v_lshlrev_b64 v[36:37], 2, v[54:55]
	v_lshl_add_u64 v[84:85], s[30:31], 0, v[36:37]
	v_lshl_add_u64 v[72:73], s[28:29], 0, v[36:37]
	s_waitcnt vmcnt(0)
	v_mfma_f32_16x16x32_bf16 v[32:35], v[130:133], v[44:47], v[32:35]
	global_load_dwordx4 v[44:47], v[84:85], off offset:256
	global_load_dwordx4 v[48:51], v[72:73], off offset:256
	v_lshl_add_u64 v[82:83], s[16:17], 0, v[36:37]
	global_load_dwordx4 v[36:39], v[82:83], off offset:256
	s_ashr_i32 s24, s7, 6
	s_ashr_i32 s25, s24, 31
	s_lshl_b64 s[24:25], s[24:25], 13
	s_add_u32 s26, s57, s24
	v_lshl_add_u64 v[80:81], v[54:55], 1, v[52:53]
	s_addc_u32 s27, s58, s25
	s_add_u32 s24, s59, s24
	s_addc_u32 s25, s60, s25
	v_exp_f32_e32 v27, v27
	s_waitcnt vmcnt(2)
	v_add_f32_e32 v32, v32, v44
	v_mul_f32_e32 v32, 0xbfb8aa3b, v32
	v_exp_f32_e32 v32, v32
	s_waitcnt vmcnt(1)
	v_add_f32_e32 v40, v40, v48
	v_mul_f32_e32 v40, 0xbfb8aa3b, v40
	v_exp_f32_e32 v40, v40
	v_add_f32_e32 v32, 1.0, v32
	v_rcp_f32_e32 v44, v32
	v_add_f32_e32 v32, v41, v49
	v_mul_f32_e32 v32, 0xbfb8aa3b, v32
	v_exp_f32_e32 v32, v32
	v_add_f32_e32 v40, 1.0, v40
	v_rcp_f32_e32 v40, v40
	s_waitcnt lgkmcnt(0)
	v_lshlrev_b32_e32 v48, 16, v56
	v_add_f32_e32 v32, 1.0, v32
	v_rcp_f32_e32 v41, v32
	v_add_f32_e32 v32, v33, v45
	v_and_b32_e32 v49, 0xffff0000, v56
	v_mul_f32_e32 v32, 0xbfb8aa3b, v32
	s_waitcnt vmcnt(0)
; #define LAS __attribute__((address_space(3)))
; __device__ __forceinline__ unsigned pk2(float lo, float hi) { return pg8::cvt_pk_bf16(lo, hi); }
; __device__ __forceinline__ float sigmoidf_(float x) { return __builtin_amdgcn_rcpf(1.0f + __expf(-x)); }
; template <bool FULL> __device__ __forceinline__ void lru_tile(const Args& a, int l, int tile, LAS unsigned char* lds, int tid, int lane, int wave) {
;     ...
;             const int c0 = e0 + 4 * fq;
;             const f32x4 ba = *(const f32x4*)(a.in[22] + (size_t)l * 256 + c0), bx = *(const f32x4*)(a.in[24] + (size_t)l * 256 + c0), c8v = *(const f32x4*)(c8t + c0);
;             const u32x2 xr = *(const LAS u32x2*)(lds + OFF_XC + ((cb * 16 + fr) * 264 + c0) * 2);
;             float lav[4];
;             const float xcv[4] = {__uint_as_float(xr.x << 16), __uint_as_float(xr.x & 0xffff0000u), __uint_as_float(xr.y << 16), __uint_as_float(xr.y & 0xffff0000u)};
; #pragma unroll
;             for (int r = 0; r < 4; ++r) {
;                 const float rg = sigmoidf_(ra[r] + ba[r]), ig = sigmoidf_(ia[r] + bx[r]);
;                 const float la = c8v[r] * rg; const float av_ = __expf(la); const float m2 = -expm1f(2.0f * la);
;                 av[et][r] = av_; bv[et][r] = sqrtf(fmaxf(m2, 0.f)) * ig * xcv[r]; lav[r] = la;
;             }
;             {
;               bf16* yr = Y + (size_t)(t0 + cb * 16 + fr) * DM + c0;
;               u32x2 wl_; wl_.x = pk2(lav[0], lav[1]); wl_.y = pk2(lav[2], lav[3]); *(u32x2*)(yr + 768) = wl_;
;               u32x2 wb_; wb_.x = pk2(bv[et][0], bv[et][1]); wb_.y = pk2(bv[et][2], bv[et][3]); *(u32x2*)(yr + 512) = wb_; }
	v_pk_mul_f32 v[40:41], v[36:37], v[40:41]
	v_exp_f32_e32 v32, v32
	v_pk_add_f32 v[36:37], v[40:41], v[40:41]
	v_add_f32_e32 v42, v42, v50
	v_mul_f32_e32 v33, 0x3fb8aa3b, v36
	v_rndne_f32_e32 v33, v33
	v_fmamk_f32 v56, v33, 0xbf317218, v36
	v_fmac_f32_e32 v56, 0x3102e308, v33
	v_fmamk_f32 v58, v56, 0x395133b1, v177
	v_cmp_eq_f32_e32 vcc, s2, v33
	v_cvt_i32_f32_e32 v33, v33
	v_fmaak_f32 v58, v56, v58, 0x3c0887f9
	v_fmaak_f32 v58, v56, v58, 0x3d2aaa81
	v_fmaak_f32 v58, v56, v58, 0x3e2aaaab
	v_fma_f32 v58, v56, v58, 0.5
	v_ldexp_f32 v33, 1.0, v33
	v_mul_f32_e32 v58, v56, v58
	v_cndmask_b32_e32 v33, v33, v195, vcc
	v_fmac_f32_e32 v56, v56, v58
	v_add_f32_e32 v58, -1.0, v33
	v_fmac_f32_e32 v58, v33, v56
	v_add_f32_e32 v33, v58, v58
	v_cndmask_b32_e32 v33, v58, v33, vcc
	v_max_f32_e64 v33, -v33, 0
	v_cmp_gt_f32_e32 vcc, s19, v33
	v_mul_f32_e32 v56, 0x4f800000, v33
	v_add_f32_e32 v34, v34, v46
	v_cndmask_b32_e32 v33, v33, v56, vcc
	v_sqrt_f32_e32 v56, v33
	v_mul_f32_e32 v42, 0xbfb8aa3b, v42
	v_mul_f32_e32 v34, 0xbfb8aa3b, v34
	v_add_f32_e32 v32, 1.0, v32
	v_add_u32_e32 v58, -1, v56
	v_fma_f32 v59, -v58, v56, v33
	v_cmp_ge_f32_e64 s[36:37], 0, v59
	v_add_u32_e32 v59, 1, v56
	v_exp_f32_e32 v42, v42
	v_cndmask_b32_e64 v58, v56, v58, s[36:37]
	v_fma_f32 v56, -v59, v56, v33
	v_cmp_lt_f32_e64 s[36:37], 0, v56
	v_exp_f32_e32 v34, v34
	v_rcp_f32_e32 v45, v32
	v_cndmask_b32_e64 v56, v58, v59, s[36:37]
	v_mul_f32_e32 v58, 0x37800000, v56
	v_cndmask_b32_e32 v56, v56, v58, vcc
	v_cmp_class_f32_e32 vcc, v33, v178
	v_add_f32_e32 v42, 1.0, v42
	v_add_f32_e32 v34, 1.0, v34
	v_cndmask_b32_e32 v33, v56, v33, vcc
	v_mul_f32_e32 v56, 0x3fb8aa3b, v37
	v_rndne_f32_e32 v56, v56
	v_fmamk_f32 v58, v56, 0xbf317218, v37
	v_fmac_f32_e32 v58, 0x3102e308, v56
	v_fmamk_f32 v59, v58, 0x395133b1, v177
	v_cmp_eq_f32_e32 vcc, s2, v56
	v_cvt_i32_f32_e32 v56, v56
	v_fmaak_f32 v59, v58, v59, 0x3c0887f9
	v_fmaak_f32 v59, v58, v59, 0x3d2aaa81
	v_fmaak_f32 v59, v58, v59, 0x3e2aaaab
	v_fma_f32 v59, v58, v59, 0.5
	v_ldexp_f32 v56, 1.0, v56
	v_mul_f32_e32 v59, v58, v59
	v_cndmask_b32_e32 v56, v56, v195, vcc
	v_fmac_f32_e32 v58, v58, v59
	v_add_f32_e32 v59, -1.0, v56
	v_fmac_f32_e32 v59, v56, v58
	v_add_f32_e32 v56, v59, v59
	v_cndmask_b32_e32 v56, v59, v56, vcc
	v_max_f32_e64 v56, -v56, 0
	v_cmp_gt_f32_e32 vcc, s19, v56
	v_mul_f32_e32 v58, 0x4f800000, v56
	v_mul_f32_e32 v32, 0x3fb8aa3b, v40
	v_cndmask_b32_e32 v56, v56, v58, vcc
	v_sqrt_f32_e32 v58, v56
	v_lshlrev_b32_e32 v46, 16, v57
	v_cvt_pk_bf16_f32 v40, v40, v41
	v_exp_f32_e32 v32, v32
	v_add_u32_e32 v59, -1, v58
	v_fma_f32 v62, -v59, v58, v56
	v_cmp_ge_f32_e64 s[36:37], 0, v62
	v_add_u32_e32 v62, 1, v58
	s_nop 0
	v_cndmask_b32_e64 v59, v58, v59, s[36:37]
	v_fma_f32 v58, -v62, v58, v56
	v_cmp_lt_f32_e64 s[36:37], 0, v58
	s_nop 1
	v_cndmask_b32_e64 v58, v59, v62, s[36:37]
	v_mul_f32_e32 v59, 0x37800000, v58
	v_cndmask_b32_e32 v58, v58, v59, vcc
	v_cmp_class_f32_e32 vcc, v56, v178
	v_or_b32_e32 v62, s7, v86
	v_mad_u32_u24 v62, v79, s12, v62
	v_cndmask_b32_e32 v56, v58, v56, vcc
	v_cmp_nlt_f32_e32 vcc, s86, v36
	v_lshl_add_u32 v62, v62, 1, s0
	s_or_b32 s7, s5, 0x60
	v_cndmask_b32_e32 v33, 0, v33, vcc
	v_cmp_nlt_f32_e32 vcc, s86, v37
	v_or_b32_e32 v74, s7, v86
	v_mad_u32_u24 v74, v79, s12, v74
	v_cndmask_b32_e32 v56, 0, v56, vcc
	v_cmp_ngt_f32_e32 vcc, s56, v37
	v_lshl_add_u32 v74, v74, 1, s0
	s_nop 0
	v_cndmask_b32_e32 v37, 1.0, v56, vcc
	v_cmp_ngt_f32_e32 vcc, s56, v36
	s_nop 1
	v_cndmask_b32_e32 v36, 1.0, v33, vcc
	v_pk_mul_f32 v[36:37], v[44:45], v[36:37]
	v_rcp_f32_e32 v44, v42
	v_rcp_f32_e32 v42, v34
	v_add_f32_e32 v34, v43, v51
	v_mul_f32_e32 v34, 0xbfb8aa3b, v34
	v_exp_f32_e32 v34, v34
	v_pk_mul_f32 v[36:37], v[36:37], v[48:49]
	v_mul_f32_e32 v33, 0x3fb8aa3b, v41
	v_exp_f32_e32 v33, v33
	v_add_f32_e32 v34, 1.0, v34
	v_rcp_f32_e32 v45, v34
	v_add_f32_e32 v34, v35, v47
	v_mul_f32_e32 v34, 0xbfb8aa3b, v34
	v_exp_f32_e32 v34, v34
	v_pk_mul_f32 v[44:45], v[38:39], v[44:45]
	v_and_b32_e32 v47, 0xffff0000, v57
	v_pk_add_f32 v[38:39], v[44:45], v[44:45]
	v_add_f32_e32 v34, 1.0, v34
	v_mul_f32_e32 v35, 0x3fb8aa3b, v38
	v_rndne_f32_e32 v35, v35
	v_fmamk_f32 v48, v35, 0xbf317218, v38
	v_fmac_f32_e32 v48, 0x3102e308, v35
	v_fmamk_f32 v49, v48, 0x395133b1, v177
	v_cmp_eq_f32_e32 vcc, s2, v35
	v_cvt_i32_f32_e32 v35, v35
	v_fmaak_f32 v49, v48, v49, 0x3c0887f9
	v_fmaak_f32 v49, v48, v49, 0x3d2aaa81
	v_fmaak_f32 v49, v48, v49, 0x3e2aaaab
	v_fma_f32 v49, v48, v49, 0.5
	v_ldexp_f32 v35, 1.0, v35
	v_mul_f32_e32 v49, v48, v49
	v_cndmask_b32_e32 v35, v35, v195, vcc
	v_fmac_f32_e32 v48, v48, v49
	v_add_f32_e32 v49, -1.0, v35
	v_fmac_f32_e32 v49, v35, v48
	v_add_f32_e32 v35, v49, v49
	v_cndmask_b32_e32 v35, v49, v35, vcc
	v_max_f32_e64 v35, -v35, 0
	v_cmp_gt_f32_e32 vcc, s19, v35
	v_mul_f32_e32 v48, 0x4f800000, v35
	v_rcp_f32_e32 v43, v34
	v_cndmask_b32_e32 v35, v35, v48, vcc
	v_sqrt_f32_e32 v48, v35
	v_cvt_pk_bf16_f32 v41, v44, v45
	global_store_dwordx2 v[80:81], v[40:41], off offset:1664
	v_cvt_pk_bf16_f32 v40, v36, v37
	v_add_u32_e32 v49, -1, v48
	v_fma_f32 v50, -v49, v48, v35
	v_cmp_ge_f32_e64 s[36:37], 0, v50
	v_add_u32_e32 v50, 1, v48
	v_mul_f32_e32 v34, 0x3fb8aa3b, v44
	v_cndmask_b32_e64 v49, v48, v49, s[36:37]
	v_fma_f32 v48, -v50, v48, v35
	v_cmp_lt_f32_e64 s[36:37], 0, v48
	v_exp_f32_e32 v34, v34
	s_nop 0
	v_cndmask_b32_e64 v48, v49, v50, s[36:37]
	v_mul_f32_e32 v49, 0x37800000, v48
	v_cndmask_b32_e32 v48, v48, v49, vcc
	v_cmp_class_f32_e32 vcc, v35, v178
	s_nop 1
	v_cndmask_b32_e32 v35, v48, v35, vcc
	v_mul_f32_e32 v48, 0x3fb8aa3b, v39
	v_rndne_f32_e32 v48, v48
	v_fmamk_f32 v49, v48, 0xbf317218, v39
	v_fmac_f32_e32 v49, 0x3102e308, v48
; #define LAS __attribute__((address_space(3)))
; __device__ __forceinline__ unsigned pk2(float lo, float hi) { return pg8::cvt_pk_bf16(lo, hi); }
; __device__ __forceinline__ float sigmoidf_(float x) { return __builtin_amdgcn_rcpf(1.0f + __expf(-x)); }
; #define MFMA16(X, Y, ACC) ACC = __builtin_amdgcn_mfma_f32_16x16x32_bf16(X, Y, ACC, 0, 0, 0)
; template <bool FULL> __device__ __forceinline__ void lru_tile(const Args& a, int l, int tile, LAS unsigned char* lds, int tid, int lane, int wave) {
;     ...
;             for (int ks = 0; ks < 2; ++ks) {
;                 const bf16x8 xv = *(const LAS bf16x8*)(lds + OFF_XC + ((cb * 16 + fr) * 264 + nb * 64 + 32 * ks + 8 * fq) * 2);
;                 const bf16x8 wa = *(const bf16x8*)(WA + (size_t)nb * 4096 + (el + fr) * 64 + 32 * ks + 8 * fq);
;                 const bf16x8 wx = *(const bf16x8*)(WX + (size_t)nb * 4096 + (el + fr) * 64 + 32 * ks + 8 * fq);
;                 MFMA16(wa, xv, ra); MFMA16(wx, xv, ia);
;     ...
;             const float xcv[4] = {__uint_as_float(xr.x << 16), __uint_as_float(xr.x & 0xffff0000u), __uint_as_float(xr.y << 16), __uint_as_float(xr.y & 0xffff0000u)};
; #pragma unroll
;             for (int r = 0; r < 4; ++r) {
;                 const float rg = sigmoidf_(ra[r] + ba[r]), ig = sigmoidf_(ia[r] + bx[r]);
;                 const float la = c8v[r] * rg; const float av_ = __expf(la); const float m2 = -expm1f(2.0f * la);
;                 av[et][r] = av_; bv[et][r] = sqrtf(fmaxf(m2, 0.f)) * ig * xcv[r]; lav[r] = la;
;             }
;             {
;               bf16* yr = Y + (size_t)(t0 + cb * 16 + fr) * DM + c0;
;               u32x2 wl_; wl_.x = pk2(lav[0], lav[1]); wl_.y = pk2(lav[2], lav[3]); *(u32x2*)(yr + 768) = wl_;
;               u32x2 wb_; wb_.x = pk2(bv[et][0], bv[et][1]); wb_.y = pk2(bv[et][2], bv[et][3]); *(u32x2*)(yr + 512) = wb_; }
	v_fmamk_f32 v50, v49, 0x395133b1, v177
	v_cmp_eq_f32_e32 vcc, s2, v48
	v_cvt_i32_f32_e32 v48, v48
	v_fmaak_f32 v50, v49, v50, 0x3c0887f9
	v_fmaak_f32 v50, v49, v50, 0x3d2aaa81
	v_fmaak_f32 v50, v49, v50, 0x3e2aaaab
	v_fma_f32 v50, v49, v50, 0.5
	v_ldexp_f32 v48, 1.0, v48
	v_mul_f32_e32 v50, v49, v50
	v_cndmask_b32_e32 v48, v48, v195, vcc
	v_fmac_f32_e32 v49, v49, v50
	v_add_f32_e32 v50, -1.0, v48
	v_fmac_f32_e32 v50, v48, v49
	v_add_f32_e32 v48, v50, v50
	v_cndmask_b32_e32 v48, v50, v48, vcc
	v_max_f32_e64 v48, -v48, 0
	v_cmp_gt_f32_e32 vcc, s19, v48
	v_mul_f32_e32 v49, 0x4f800000, v48
	s_nop 0
	v_cndmask_b32_e32 v48, v48, v49, vcc
	v_sqrt_f32_e32 v49, v48
	s_nop 0
	v_add_u32_e32 v50, -1, v49
	v_fma_f32 v51, -v50, v49, v48
	v_cmp_ge_f32_e64 s[36:37], 0, v51
	v_add_u32_e32 v51, 1, v49
	s_nop 0
	v_cndmask_b32_e64 v50, v49, v50, s[36:37]
	v_fma_f32 v49, -v51, v49, v48
	v_cmp_lt_f32_e64 s[36:37], 0, v49
	s_nop 1
	v_cndmask_b32_e64 v49, v50, v51, s[36:37]
	v_mul_f32_e32 v50, 0x37800000, v49
	v_cndmask_b32_e32 v49, v49, v50, vcc
	v_cmp_class_f32_e32 vcc, v48, v178
	s_nop 1
	v_cndmask_b32_e32 v48, v49, v48, vcc
	v_cmp_nlt_f32_e32 vcc, s86, v38
	s_nop 1
	v_cndmask_b32_e32 v35, 0, v35, vcc
	v_cmp_nlt_f32_e32 vcc, s86, v39
	s_nop 1
	v_cndmask_b32_e32 v48, 0, v48, vcc
	v_cmp_ngt_f32_e32 vcc, s56, v39
	s_nop 1
	v_cndmask_b32_e32 v39, 1.0, v48, vcc
	v_cmp_ngt_f32_e32 vcc, s56, v38
	s_nop 1
	v_cndmask_b32_e32 v38, 1.0, v35, vcc
	v_pk_mul_f32 v[38:39], v[42:43], v[38:39]
	v_mul_f32_e32 v35, 0x3fb8aa3b, v45
	v_pk_mul_f32 v[38:39], v[38:39], v[46:47]
	v_exp_f32_e32 v35, v35
	v_cvt_pk_bf16_f32 v41, v38, v39
	global_store_dwordx2 v[80:81], v[40:41], off offset:1152
	v_lshl_add_u64 v[40:41], s[26:27], 0, v[144:145]
	v_lshl_add_u64 v[52:53], v[40:41], 0, v[68:69]
	global_load_dwordx4 v[118:121], v[52:53], off offset:2048
	global_load_dwordx4 v[122:125], v[52:53], off offset:2112
	v_lshl_add_u64 v[40:41], s[24:25], 0, v[144:145]
	v_lshl_add_u64 v[56:57], v[40:41], 0, v[68:69]
	global_load_dwordx4 v[126:129], v[56:57], off offset:2048
	global_load_dwordx4 v[130:133], v[56:57], off offset:2112
	ds_read_b128 v[40:43], v87
	s_waitcnt vmcnt(3) lgkmcnt(0)
	v_mfma_f32_16x16x32_bf16 v[44:47], v[118:121], v[40:43], 0
	s_ashr_i32 s24, s7, 6
	s_ashr_i32 s25, s24, 31
	s_lshl_b64 s[24:25], s[24:25], 13
	s_waitcnt vmcnt(1)
	v_mfma_f32_16x16x32_bf16 v[40:43], v[126:129], v[40:43], 0
	ds_read_b128 v[48:51], v87 offset:64
	s_nop 0
	s_add_u32 s26, s57, s24
	s_waitcnt vmcnt(1) lgkmcnt(0)
	v_mfma_f32_16x16x32_bf16 v[52:55], v[122:125], v[48:51], v[44:47]
	s_addc_u32 s27, s58, s25
	s_add_u32 s24, s59, s24
	s_addc_u32 s25, s60, s25
	s_waitcnt vmcnt(0)
	v_mfma_f32_16x16x32_bf16 v[44:47], v[130:133], v[48:51], v[40:43]
	global_load_dwordx4 v[56:59], v[72:73], off offset:320
	global_load_dwordx4 v[48:51], v[84:85], off offset:320
	s_nop 0
	global_load_dwordx4 v[40:43], v[82:83], off offset:320
	ds_read_b64 v[62:63], v62
	s_or_b32 s5, s5, 0x70
	v_or_b32_e32 v86, s5, v86
	v_mad_u32_u24 v79, v79, s12, v86
	v_lshl_add_u32 v79, v79, 1, s0
	s_waitcnt vmcnt(2)
	v_add_f32_e32 v52, v52, v56
	s_waitcnt vmcnt(1)
	v_add_f32_e32 v44, v44, v48
	v_add_f32_e32 v48, v53, v57
	v_mul_f32_e32 v52, 0xbfb8aa3b, v52
	v_mul_f32_e32 v48, 0xbfb8aa3b, v48
	v_exp_f32_e32 v52, v52
	v_exp_f32_e32 v48, v48
	v_add_f32_e32 v45, v45, v49
	s_waitcnt lgkmcnt(0)
	v_lshlrev_b32_e32 v56, 16, v62
	v_add_f32_e32 v52, 1.0, v52
	v_add_f32_e32 v48, 1.0, v48
	v_rcp_f32_e32 v52, v52
	v_rcp_f32_e32 v53, v48
	v_and_b32_e32 v57, 0xffff0000, v62
	v_mul_f32_e32 v44, 0xbfb8aa3b, v44
	v_mul_f32_e32 v45, 0xbfb8aa3b, v45
	s_waitcnt vmcnt(0)
	v_pk_mul_f32 v[48:49], v[40:41], v[52:53]
	v_exp_f32_e32 v44, v44
	v_pk_add_f32 v[52:53], v[48:49], v[48:49]
	v_exp_f32_e32 v45, v45
	v_mul_f32_e32 v41, 0x3fb8aa3b, v52
	v_rndne_f32_e32 v41, v41
	v_fmamk_f32 v62, v41, 0xbf317218, v52
	v_fmac_f32_e32 v62, 0x3102e308, v41
	v_fmamk_f32 v64, v62, 0x395133b1, v177
	v_cmp_eq_f32_e32 vcc, s2, v41
	v_cvt_i32_f32_e32 v41, v41
	v_fmaak_f32 v64, v62, v64, 0x3c0887f9
	v_fmaak_f32 v64, v62, v64, 0x3d2aaa81
	v_fmaak_f32 v64, v62, v64, 0x3e2aaaab
	v_fma_f32 v64, v62, v64, 0.5
	v_ldexp_f32 v41, 1.0, v41
	v_mul_f32_e32 v64, v62, v64
	v_cndmask_b32_e32 v41, v41, v195, vcc
	v_fmac_f32_e32 v62, v62, v64
	v_add_f32_e32 v64, -1.0, v41
	v_fmac_f32_e32 v64, v41, v62
	v_add_f32_e32 v41, v64, v64
	v_cndmask_b32_e32 v41, v64, v41, vcc
	v_max_f32_e64 v41, -v41, 0
	v_cmp_gt_f32_e32 vcc, s19, v41
	v_mul_f32_e32 v62, 0x4f800000, v41
	v_add_f32_e32 v44, 1.0, v44
	v_cndmask_b32_e32 v41, v41, v62, vcc
	v_sqrt_f32_e32 v62, v41
	v_add_f32_e32 v45, 1.0, v45
	v_rcp_f32_e32 v44, v44
	v_rcp_f32_e32 v45, v45
	v_add_u32_e32 v64, -1, v62
	v_fma_f32 v65, -v64, v62, v41
	v_cmp_ge_f32_e64 s[36:37], 0, v65
	v_add_u32_e32 v65, 1, v62
	v_add_f32_e32 v46, v46, v50
	v_cndmask_b32_e64 v64, v62, v64, s[36:37]
	v_fma_f32 v62, -v65, v62, v41
	v_cmp_lt_f32_e64 s[36:37], 0, v62
	v_add_f32_e32 v50, v55, v59
	v_mul_f32_e32 v50, 0xbfb8aa3b, v50
	v_cndmask_b32_e64 v62, v64, v65, s[36:37]
	v_mul_f32_e32 v64, 0x37800000, v62
	v_cndmask_b32_e32 v62, v62, v64, vcc
	v_cmp_class_f32_e32 vcc, v41, v178
	v_exp_f32_e32 v50, v50
	v_add_f32_e32 v47, v47, v51
	v_cndmask_b32_e32 v41, v62, v41, vcc
	v_mul_f32_e32 v62, 0x3fb8aa3b, v53
	v_rndne_f32_e32 v62, v62
	v_fmamk_f32 v64, v62, 0xbf317218, v53
	v_fmac_f32_e32 v64, 0x3102e308, v62
	v_fmamk_f32 v65, v64, 0x395133b1, v177
	v_cmp_eq_f32_e32 vcc, s2, v62
	v_cvt_i32_f32_e32 v62, v62
	v_fmaak_f32 v65, v64, v65, 0x3c0887f9
	v_fmaak_f32 v65, v64, v65, 0x3d2aaa81
	v_fmaak_f32 v65, v64, v65, 0x3e2aaaab
	v_fma_f32 v65, v64, v65, 0.5
	v_ldexp_f32 v62, 1.0, v62
	v_mul_f32_e32 v65, v64, v65
; #define LAS __attribute__((address_space(3)))
; __device__ __forceinline__ unsigned pk2(float lo, float hi) { return pg8::cvt_pk_bf16(lo, hi); }
; __device__ __forceinline__ float sigmoidf_(float x) { return __builtin_amdgcn_rcpf(1.0f + __expf(-x)); }
; #define MFMA16(X, Y, ACC) ACC = __builtin_amdgcn_mfma_f32_16x16x32_bf16(X, Y, ACC, 0, 0, 0)
; template <bool FULL> __device__ __forceinline__ void lru_tile(const Args& a, int l, int tile, LAS unsigned char* lds, int tid, int lane, int wave) {
;     ...
;             for (int ks = 0; ks < 2; ++ks) {
;                 const bf16x8 xv = *(const LAS bf16x8*)(lds + OFF_XC + ((cb * 16 + fr) * 264 + nb * 64 + 32 * ks + 8 * fq) * 2);
;                 const bf16x8 wa = *(const bf16x8*)(WA + (size_t)nb * 4096 + (el + fr) * 64 + 32 * ks + 8 * fq);
;                 const bf16x8 wx = *(const bf16x8*)(WX + (size_t)nb * 4096 + (el + fr) * 64 + 32 * ks + 8 * fq);
;                 MFMA16(wa, xv, ra); MFMA16(wx, xv, ia);
;     ...
;             const float xcv[4] = {__uint_as_float(xr.x << 16), __uint_as_float(xr.x & 0xffff0000u), __uint_as_float(xr.y << 16), __uint_as_float(xr.y & 0xffff0000u)};
; #pragma unroll
;             for (int r = 0; r < 4; ++r) {
;                 const float rg = sigmoidf_(ra[r] + ba[r]), ig = sigmoidf_(ia[r] + bx[r]);
;                 const float la = c8v[r] * rg; const float av_ = __expf(la); const float m2 = -expm1f(2.0f * la);
;                 av[et][r] = av_; bv[et][r] = sqrtf(fmaxf(m2, 0.f)) * ig * xcv[r]; lav[r] = la;
;             }
;             {
;               bf16* yr = Y + (size_t)(t0 + cb * 16 + fr) * DM + c0;
;               u32x2 wl_; wl_.x = pk2(lav[0], lav[1]); wl_.y = pk2(lav[2], lav[3]); *(u32x2*)(yr + 768) = wl_;
;               u32x2 wb_; wb_.x = pk2(bv[et][0], bv[et][1]); wb_.y = pk2(bv[et][2], bv[et][3]); *(u32x2*)(yr + 512) = wb_; }
	v_cndmask_b32_e32 v62, v62, v195, vcc
	v_fmac_f32_e32 v64, v64, v65
	v_add_f32_e32 v65, -1.0, v62
	v_fmac_f32_e32 v65, v62, v64
	v_add_f32_e32 v62, v65, v65
	v_cndmask_b32_e32 v62, v65, v62, vcc
	v_max_f32_e64 v62, -v62, 0
	v_cmp_gt_f32_e32 vcc, s19, v62
	v_mul_f32_e32 v64, 0x4f800000, v62
	v_add_f32_e32 v50, 1.0, v50
	v_cndmask_b32_e32 v62, v62, v64, vcc
	v_sqrt_f32_e32 v64, v62
	v_mul_f32_e32 v46, 0xbfb8aa3b, v46
	v_mul_f32_e32 v47, 0xbfb8aa3b, v47
	v_exp_f32_e32 v46, v46
	v_add_u32_e32 v65, -1, v64
	v_fma_f32 v66, -v65, v64, v62
	v_cmp_ge_f32_e64 s[36:37], 0, v66
	v_add_u32_e32 v66, 1, v64
	v_exp_f32_e32 v47, v47
	v_cndmask_b32_e64 v65, v64, v65, s[36:37]
	v_fma_f32 v64, -v66, v64, v62
	v_cmp_lt_f32_e64 s[36:37], 0, v64
	v_add_f32_e32 v46, 1.0, v46
	v_add_f32_e32 v47, 1.0, v47
	v_cndmask_b32_e64 v64, v65, v66, s[36:37]
	v_mul_f32_e32 v65, 0x37800000, v64
	v_cndmask_b32_e32 v64, v64, v65, vcc
	v_cmp_class_f32_e32 vcc, v62, v178
	v_rcp_f32_e32 v46, v46
	v_rcp_f32_e32 v47, v47
	v_cndmask_b32_e32 v62, v64, v62, vcc
	v_cmp_nlt_f32_e32 vcc, s86, v52
	v_mul_f32_e32 v40, 0x3fb8aa3b, v48
	v_and_b32_e32 v51, 0xffff0000, v63
	v_cndmask_b32_e32 v41, 0, v41, vcc
	v_cmp_nlt_f32_e32 vcc, s86, v53
	v_cvt_pk_bf16_f32 v48, v48, v49
	v_exp_f32_e32 v40, v40
	s_nop 0
	v_cndmask_b32_e32 v62, 0, v62, vcc
	v_cmp_ngt_f32_e32 vcc, s56, v53
	s_nop 1
	v_cndmask_b32_e32 v53, 1.0, v62, vcc
	v_cmp_ngt_f32_e32 vcc, s56, v52
	s_nop 1
	v_cndmask_b32_e32 v52, 1.0, v41, vcc
	v_pk_mul_f32 v[44:45], v[44:45], v[52:53]
	v_add_f32_e32 v52, v54, v58
	v_mul_f32_e32 v52, 0xbfb8aa3b, v52
	v_exp_f32_e32 v52, v52
	v_rcp_f32_e32 v53, v50
	v_pk_mul_f32 v[44:45], v[44:45], v[56:57]
	v_mul_f32_e32 v41, 0x3fb8aa3b, v49
	v_add_f32_e32 v52, 1.0, v52
	v_rcp_f32_e32 v52, v52
	v_lshlrev_b32_e32 v50, 16, v63
	v_exp_f32_e32 v41, v41
	v_pk_mul_f32 v[52:53], v[42:43], v[52:53]
	s_nop 0
	v_pk_add_f32 v[54:55], v[52:53], v[52:53]
	v_cvt_pk_bf16_f32 v49, v52, v53
	global_store_dwordx2 v[80:81], v[48:49], off offset:1696
	v_mul_f32_e32 v43, 0x3fb8aa3b, v54
	v_rndne_f32_e32 v43, v43
	v_fmamk_f32 v56, v43, 0xbf317218, v54
	v_fmac_f32_e32 v56, 0x3102e308, v43
	v_fmamk_f32 v57, v56, 0x395133b1, v177
	v_cmp_eq_f32_e32 vcc, s2, v43
	v_cvt_i32_f32_e32 v43, v43
	v_fmaak_f32 v57, v56, v57, 0x3c0887f9
	v_fmaak_f32 v57, v56, v57, 0x3d2aaa81
	v_fmaak_f32 v57, v56, v57, 0x3e2aaaab
	v_fma_f32 v57, v56, v57, 0.5
	v_ldexp_f32 v43, 1.0, v43
	v_mul_f32_e32 v57, v56, v57
	v_cndmask_b32_e32 v43, v43, v195, vcc
	v_fmac_f32_e32 v56, v56, v57
	v_add_f32_e32 v57, -1.0, v43
	v_fmac_f32_e32 v57, v43, v56
	v_add_f32_e32 v43, v57, v57
	v_cndmask_b32_e32 v43, v57, v43, vcc
	v_max_f32_e64 v43, -v43, 0
	v_cmp_gt_f32_e32 vcc, s19, v43
	v_mul_f32_e32 v56, 0x4f800000, v43
	v_cvt_pk_bf16_f32 v48, v44, v45
	v_mul_f32_e32 v42, 0x3fb8aa3b, v52
	v_cndmask_b32_e32 v43, v43, v56, vcc
	v_sqrt_f32_e32 v56, v43
	v_exp_f32_e32 v42, v42
	v_add_u32_e32 v57, -1, v56
	v_fma_f32 v58, -v57, v56, v43
	v_cmp_ge_f32_e64 s[36:37], 0, v58
	v_add_u32_e32 v58, 1, v56
	s_nop 0
	v_cndmask_b32_e64 v57, v56, v57, s[36:37]
	v_fma_f32 v56, -v58, v56, v43
	v_cmp_lt_f32_e64 s[36:37], 0, v56
	s_nop 1
	v_cndmask_b32_e64 v56, v57, v58, s[36:37]
	v_mul_f32_e32 v57, 0x37800000, v56
	v_cndmask_b32_e32 v56, v56, v57, vcc
	v_cmp_class_f32_e32 vcc, v43, v178
	s_nop 1
	v_cndmask_b32_e32 v43, v56, v43, vcc
	v_mul_f32_e32 v56, 0x3fb8aa3b, v55
	v_rndne_f32_e32 v56, v56
	v_fmamk_f32 v57, v56, 0xbf317218, v55
	v_fmac_f32_e32 v57, 0x3102e308, v56
	v_fmamk_f32 v58, v57, 0x395133b1, v177
	v_cmp_eq_f32_e32 vcc, s2, v56
	v_cvt_i32_f32_e32 v56, v56
	v_fmaak_f32 v58, v57, v58, 0x3c0887f9
	v_fmaak_f32 v58, v57, v58, 0x3d2aaa81
	v_fmaak_f32 v58, v57, v58, 0x3e2aaaab
	v_fma_f32 v58, v57, v58, 0.5
	v_ldexp_f32 v56, 1.0, v56
	v_mul_f32_e32 v58, v57, v58
	v_cndmask_b32_e32 v56, v56, v195, vcc
	v_fmac_f32_e32 v57, v57, v58
	v_add_f32_e32 v58, -1.0, v56
	v_fmac_f32_e32 v58, v56, v57
	v_add_f32_e32 v56, v58, v58
	v_cndmask_b32_e32 v56, v58, v56, vcc
	v_max_f32_e64 v56, -v56, 0
	v_cmp_gt_f32_e32 vcc, s19, v56
	v_mul_f32_e32 v57, 0x4f800000, v56
	s_nop 0
	v_cndmask_b32_e32 v56, v56, v57, vcc
	v_sqrt_f32_e32 v57, v56
	s_nop 0
	v_add_u32_e32 v58, -1, v57
	v_fma_f32 v59, -v58, v57, v56
	v_cmp_ge_f32_e64 s[36:37], 0, v59
	v_add_u32_e32 v59, 1, v57
	s_nop 0
	v_cndmask_b32_e64 v58, v57, v58, s[36:37]
	v_fma_f32 v57, -v59, v57, v56
	v_cmp_lt_f32_e64 s[36:37], 0, v57
	s_nop 1
	v_cndmask_b32_e64 v57, v58, v59, s[36:37]
	v_mul_f32_e32 v58, 0x37800000, v57
	v_cndmask_b32_e32 v57, v57, v58, vcc
	v_cmp_class_f32_e32 vcc, v56, v178
	s_nop 1
	v_cndmask_b32_e32 v56, v57, v56, vcc
	v_cmp_nlt_f32_e32 vcc, s86, v54
	s_nop 1
	v_cndmask_b32_e32 v43, 0, v43, vcc
	v_cmp_nlt_f32_e32 vcc, s86, v55
	s_nop 1
	v_cndmask_b32_e32 v56, 0, v56, vcc
	v_cmp_ngt_f32_e32 vcc, s56, v55
	s_nop 1
	v_cndmask_b32_e32 v55, 1.0, v56, vcc
	v_cmp_ngt_f32_e32 vcc, s56, v54
	s_nop 1
	v_cndmask_b32_e32 v54, 1.0, v43, vcc
	v_pk_mul_f32 v[46:47], v[46:47], v[54:55]
	v_mul_f32_e32 v43, 0x3fb8aa3b, v53
	v_pk_mul_f32 v[46:47], v[46:47], v[50:51]
	v_exp_f32_e32 v43, v43
	v_cvt_pk_bf16_f32 v49, v46, v47
	global_store_dwordx2 v[80:81], v[48:49], off offset:1184
	v_lshl_add_u64 v[48:49], s[26:27], 0, v[60:61]
	v_lshl_add_u64 v[62:63], v[48:49], 0, v[68:69]
	global_load_dwordx4 v[118:121], v[62:63], off
	global_load_dwordx4 v[122:125], v[62:63], off offset:64
	v_lshl_add_u64 v[48:49], s[24:25], 0, v[60:61]
	v_lshl_add_u64 v[64:65], v[48:49], 0, v[68:69]
	global_load_dwordx4 v[126:129], v[64:65], off
	global_load_dwordx4 v[130:133], v[64:65], off offset:64
	ds_read_b128 v[48:51], v87
	s_waitcnt vmcnt(3) lgkmcnt(0)
; #define LAS __attribute__((address_space(3)))
; __device__ __forceinline__ unsigned pk2(float lo, float hi) { return pg8::cvt_pk_bf16(lo, hi); }
; __device__ __forceinline__ float sigmoidf_(float x) { return __builtin_amdgcn_rcpf(1.0f + __expf(-x)); }
; #define MFMA16(X, Y, ACC) ACC = __builtin_amdgcn_mfma_f32_16x16x32_bf16(X, Y, ACC, 0, 0, 0)
; template <bool FULL> __device__ __forceinline__ void lru_tile(const Args& a, int l, int tile, LAS unsigned char* lds, int tid, int lane, int wave) {
;     ...
;             for (int ks = 0; ks < 2; ++ks) {
;                 const bf16x8 xv = *(const LAS bf16x8*)(lds + OFF_XC + ((cb * 16 + fr) * 264 + nb * 64 + 32 * ks + 8 * fq) * 2);
;                 const bf16x8 wa = *(const bf16x8*)(WA + (size_t)nb * 4096 + (el + fr) * 64 + 32 * ks + 8 * fq);
;                 const bf16x8 wx = *(const bf16x8*)(WX + (size_t)nb * 4096 + (el + fr) * 64 + 32 * ks + 8 * fq);
;                 MFMA16(wa, xv, ra); MFMA16(wx, xv, ia);
;             }
;             const int c0 = e0 + 4 * fq;
;             const f32x4 ba = *(const f32x4*)(a.in[22] + (size_t)l * 256 + c0), bx = *(const f32x4*)(a.in[24] + (size_t)l * 256 + c0), c8v = *(const f32x4*)(c8t + c0);
;             const u32x2 xr = *(const LAS u32x2*)(lds + OFF_XC + ((cb * 16 + fr) * 264 + c0) * 2);
;             float lav[4];
;             const float xcv[4] = {__uint_as_float(xr.x << 16), __uint_as_float(xr.x & 0xffff0000u), __uint_as_float(xr.y << 16), __uint_as_float(xr.y & 0xffff0000u)};
; #pragma unroll
;             for (int r = 0; r < 4; ++r) {
;                 const float rg = sigmoidf_(ra[r] + ba[r]), ig = sigmoidf_(ia[r] + bx[r]);
;                 const float la = c8v[r] * rg; const float av_ = __expf(la); const float m2 = -expm1f(2.0f * la);
;                 av[et][r] = av_; bv[et][r] = sqrtf(fmaxf(m2, 0.f)) * ig * xcv[r]; lav[r] = la;
;             }
;             {
;               bf16* yr = Y + (size_t)(t0 + cb * 16 + fr) * DM + c0;
;               u32x2 wl_; wl_.x = pk2(lav[0], lav[1]); wl_.y = pk2(lav[2], lav[3]); *(u32x2*)(yr + 768) = wl_;
;               u32x2 wb_; wb_.x = pk2(bv[et][0], bv[et][1]); wb_.y = pk2(bv[et][2], bv[et][3]); *(u32x2*)(yr + 512) = wb_; }
	v_mfma_f32_16x16x32_bf16 v[52:55], v[118:121], v[48:51], 0
	s_ashr_i32 s24, s5, 6
	s_ashr_i32 s25, s24, 31
	s_lshl_b64 s[24:25], s[24:25], 13
	s_waitcnt vmcnt(1)
	v_mfma_f32_16x16x32_bf16 v[48:51], v[126:129], v[48:51], 0
	ds_read_b128 v[56:59], v87 offset:64
	s_nop 0
	s_add_u32 s26, s57, s24
	s_waitcnt vmcnt(1) lgkmcnt(0)
	v_mfma_f32_16x16x32_bf16 v[60:63], v[122:125], v[56:59], v[52:55]
	s_addc_u32 s27, s58, s25
	s_add_u32 s24, s59, s24
	s_addc_u32 s25, s60, s25
	s_waitcnt vmcnt(0)
	v_mfma_f32_16x16x32_bf16 v[52:55], v[130:133], v[56:59], v[48:51]
	global_load_dwordx4 v[64:67], v[72:73], off offset:384
	global_load_dwordx4 v[56:59], v[84:85], off offset:384
	s_nop 0
	global_load_dwordx4 v[48:51], v[82:83], off offset:384
	ds_read_b64 v[74:75], v74
	s_lshl_b32 s1, s1, 14
	s_lshl_b32 s4, s4, 9
	s_add_i32 s1, s1, s4
	s_waitcnt vmcnt(2)
	v_add_f32_e32 v60, v60, v64
	s_waitcnt vmcnt(1)
	v_add_f32_e32 v52, v52, v56
	v_add_f32_e32 v56, v61, v65
	v_mul_f32_e32 v60, 0xbfb8aa3b, v60
	v_mul_f32_e32 v56, 0xbfb8aa3b, v56
	v_exp_f32_e32 v60, v60
	v_exp_f32_e32 v56, v56
	v_add_f32_e32 v53, v53, v57
	s_waitcnt lgkmcnt(0)
	v_lshlrev_b32_e32 v64, 16, v74
	v_add_f32_e32 v60, 1.0, v60
	v_add_f32_e32 v56, 1.0, v56
	v_rcp_f32_e32 v60, v60
	v_rcp_f32_e32 v61, v56
	v_and_b32_e32 v65, 0xffff0000, v74
	v_mul_f32_e32 v52, 0xbfb8aa3b, v52
	v_mul_f32_e32 v53, 0xbfb8aa3b, v53
	s_waitcnt vmcnt(0)
	v_pk_mul_f32 v[56:57], v[48:49], v[60:61]
	v_exp_f32_e32 v52, v52
	v_pk_add_f32 v[60:61], v[56:57], v[56:57]
	v_exp_f32_e32 v53, v53
	v_mul_f32_e32 v49, 0x3fb8aa3b, v60
	v_rndne_f32_e32 v49, v49
	v_fmamk_f32 v74, v49, 0xbf317218, v60
	v_fmac_f32_e32 v74, 0x3102e308, v49
	v_fmamk_f32 v88, v74, 0x395133b1, v177
	v_cmp_eq_f32_e32 vcc, s2, v49
	v_cvt_i32_f32_e32 v49, v49
	v_fmaak_f32 v88, v74, v88, 0x3c0887f9
	v_fmaak_f32 v88, v74, v88, 0x3d2aaa81
	v_fmaak_f32 v88, v74, v88, 0x3e2aaaab
	v_fma_f32 v88, v74, v88, 0.5
	v_ldexp_f32 v49, 1.0, v49
	v_mul_f32_e32 v88, v74, v88
	v_cndmask_b32_e32 v49, v49, v195, vcc
	v_fmac_f32_e32 v74, v74, v88
	v_add_f32_e32 v88, -1.0, v49
	v_fmac_f32_e32 v88, v49, v74
	v_add_f32_e32 v49, v88, v88
	v_cndmask_b32_e32 v49, v88, v49, vcc
	v_max_f32_e64 v49, -v49, 0
	v_cmp_gt_f32_e32 vcc, s19, v49
	v_mul_f32_e32 v74, 0x4f800000, v49
	v_add_f32_e32 v52, 1.0, v52
	v_cndmask_b32_e32 v49, v49, v74, vcc
	v_sqrt_f32_e32 v74, v49
	v_add_f32_e32 v53, 1.0, v53
	v_rcp_f32_e32 v52, v52
	v_rcp_f32_e32 v53, v53
	v_add_u32_e32 v88, -1, v74
	v_fma_f32 v89, -v88, v74, v49
	v_cmp_ge_f32_e64 s[36:37], 0, v89
	v_add_u32_e32 v89, 1, v74
	v_add_f32_e32 v54, v54, v58
	v_cndmask_b32_e64 v88, v74, v88, s[36:37]
	v_fma_f32 v74, -v89, v74, v49
	v_cmp_lt_f32_e64 s[36:37], 0, v74
	v_add_f32_e32 v58, v63, v67
	v_mul_f32_e32 v58, 0xbfb8aa3b, v58
	v_cndmask_b32_e64 v74, v88, v89, s[36:37]
	v_mul_f32_e32 v88, 0x37800000, v74
	v_cndmask_b32_e32 v74, v74, v88, vcc
	v_cmp_class_f32_e32 vcc, v49, v178
	v_exp_f32_e32 v58, v58
	v_add_f32_e32 v55, v55, v59
	v_cndmask_b32_e32 v49, v74, v49, vcc
	v_mul_f32_e32 v74, 0x3fb8aa3b, v61
	v_rndne_f32_e32 v74, v74
	v_fmamk_f32 v88, v74, 0xbf317218, v61
	v_fmac_f32_e32 v88, 0x3102e308, v74
	v_fmamk_f32 v89, v88, 0x395133b1, v177
	v_cmp_eq_f32_e32 vcc, s2, v74
	v_cvt_i32_f32_e32 v74, v74
	v_fmaak_f32 v89, v88, v89, 0x3c0887f9
	v_fmaak_f32 v89, v88, v89, 0x3d2aaa81
	v_fmaak_f32 v89, v88, v89, 0x3e2aaaab
	v_fma_f32 v89, v88, v89, 0.5
	v_ldexp_f32 v74, 1.0, v74
	v_mul_f32_e32 v89, v88, v89
	v_cndmask_b32_e32 v74, v74, v195, vcc
	v_fmac_f32_e32 v88, v88, v89
	v_add_f32_e32 v89, -1.0, v74
	v_fmac_f32_e32 v89, v74, v88
	v_add_f32_e32 v74, v89, v89
	v_cndmask_b32_e32 v74, v89, v74, vcc
	v_max_f32_e64 v74, -v74, 0
	v_cmp_gt_f32_e32 vcc, s19, v74
	v_mul_f32_e32 v88, 0x4f800000, v74
	v_add_f32_e32 v58, 1.0, v58
	v_cndmask_b32_e32 v74, v74, v88, vcc
	v_sqrt_f32_e32 v88, v74
	v_mul_f32_e32 v54, 0xbfb8aa3b, v54
	v_mul_f32_e32 v55, 0xbfb8aa3b, v55
	v_exp_f32_e32 v54, v54
	v_add_u32_e32 v89, -1, v88
	v_fma_f32 v90, -v89, v88, v74
	v_cmp_ge_f32_e64 s[36:37], 0, v90
	v_add_u32_e32 v90, 1, v88
	v_exp_f32_e32 v55, v55
	v_cndmask_b32_e64 v89, v88, v89, s[36:37]
	v_fma_f32 v88, -v90, v88, v74
	v_cmp_lt_f32_e64 s[36:37], 0, v88
	v_add_f32_e32 v54, 1.0, v54
	v_add_f32_e32 v55, 1.0, v55
	v_cndmask_b32_e64 v88, v89, v90, s[36:37]
	v_mul_f32_e32 v89, 0x37800000, v88
	v_cndmask_b32_e32 v88, v88, v89, vcc
	v_cmp_class_f32_e32 vcc, v74, v178
	v_rcp_f32_e32 v54, v54
	v_rcp_f32_e32 v55, v55
	v_cndmask_b32_e32 v74, v88, v74, vcc
	v_cmp_nlt_f32_e32 vcc, s86, v60
	v_mul_f32_e32 v48, 0x3fb8aa3b, v56
	v_and_b32_e32 v59, 0xffff0000, v75
	v_cndmask_b32_e32 v49, 0, v49, vcc
	v_cmp_nlt_f32_e32 vcc, s86, v61
	v_cvt_pk_bf16_f32 v56, v56, v57
	v_exp_f32_e32 v48, v48
	s_nop 0
	v_cndmask_b32_e32 v74, 0, v74, vcc
	v_cmp_ngt_f32_e32 vcc, s56, v61
	s_nop 1
	v_cndmask_b32_e32 v61, 1.0, v74, vcc
	v_cmp_ngt_f32_e32 vcc, s56, v60
	s_nop 1
	v_cndmask_b32_e32 v60, 1.0, v49, vcc
	v_pk_mul_f32 v[52:53], v[52:53], v[60:61]
	v_add_f32_e32 v60, v62, v66
	v_mul_f32_e32 v60, 0xbfb8aa3b, v60
	v_exp_f32_e32 v60, v60
	v_rcp_f32_e32 v61, v58
	v_pk_mul_f32 v[52:53], v[52:53], v[64:65]
	v_mul_f32_e32 v49, 0x3fb8aa3b, v57
	v_add_f32_e32 v60, 1.0, v60
	v_rcp_f32_e32 v60, v60
	v_lshlrev_b32_e32 v58, 16, v75
	v_exp_f32_e32 v49, v49
	v_pk_mul_f32 v[60:61], v[50:51], v[60:61]
	s_nop 0
	v_pk_add_f32 v[62:63], v[60:61], v[60:61]
	v_cvt_pk_bf16_f32 v57, v60, v61
	global_store_dwordx2 v[80:81], v[56:57], off offset:1728
	v_mul_f32_e32 v51, 0x3fb8aa3b, v62
	v_rndne_f32_e32 v51, v51
	v_fmamk_f32 v64, v51, 0xbf317218, v62
	v_fmac_f32_e32 v64, 0x3102e308, v51
	v_fmamk_f32 v65, v64, 0x395133b1, v177
	v_cmp_eq_f32_e32 vcc, s2, v51
; #define LAS __attribute__((address_space(3)))
; __device__ __forceinline__ unsigned pk2(float lo, float hi) { return pg8::cvt_pk_bf16(lo, hi); }
; __device__ __forceinline__ float sigmoidf_(float x) { return __builtin_amdgcn_rcpf(1.0f + __expf(-x)); }
; #define MFMA16(X, Y, ACC) ACC = __builtin_amdgcn_mfma_f32_16x16x32_bf16(X, Y, ACC, 0, 0, 0)
; template <bool FULL> __device__ __forceinline__ void lru_tile(const Args& a, int l, int tile, LAS unsigned char* lds, int tid, int lane, int wave) {
;     ...
;             for (int ks = 0; ks < 2; ++ks) {
;                 const bf16x8 xv = *(const LAS bf16x8*)(lds + OFF_XC + ((cb * 16 + fr) * 264 + nb * 64 + 32 * ks + 8 * fq) * 2);
;                 const bf16x8 wa = *(const bf16x8*)(WA + (size_t)nb * 4096 + (el + fr) * 64 + 32 * ks + 8 * fq);
;                 const bf16x8 wx = *(const bf16x8*)(WX + (size_t)nb * 4096 + (el + fr) * 64 + 32 * ks + 8 * fq);
;                 MFMA16(wa, xv, ra); MFMA16(wx, xv, ia);
;             }
;             const int c0 = e0 + 4 * fq;
;             const f32x4 ba = *(const f32x4*)(a.in[22] + (size_t)l * 256 + c0), bx = *(const f32x4*)(a.in[24] + (size_t)l * 256 + c0), c8v = *(const f32x4*)(c8t + c0);
;             const u32x2 xr = *(const LAS u32x2*)(lds + OFF_XC + ((cb * 16 + fr) * 264 + c0) * 2);
;     ...
;             const float xcv[4] = {__uint_as_float(xr.x << 16), __uint_as_float(xr.x & 0xffff0000u), __uint_as_float(xr.y << 16), __uint_as_float(xr.y & 0xffff0000u)};
; #pragma unroll
;             for (int r = 0; r < 4; ++r) {
;                 const float rg = sigmoidf_(ra[r] + ba[r]), ig = sigmoidf_(ia[r] + bx[r]);
;                 const float la = c8v[r] * rg; const float av_ = __expf(la); const float m2 = -expm1f(2.0f * la);
;                 av[et][r] = av_; bv[et][r] = sqrtf(fmaxf(m2, 0.f)) * ig * xcv[r]; lav[r] = la;
;             }
;             {
;               bf16* yr = Y + (size_t)(t0 + cb * 16 + fr) * DM + c0;
;               u32x2 wl_; wl_.x = pk2(lav[0], lav[1]); wl_.y = pk2(lav[2], lav[3]); *(u32x2*)(yr + 768) = wl_;
;               u32x2 wb_; wb_.x = pk2(bv[et][0], bv[et][1]); wb_.y = pk2(bv[et][2], bv[et][3]); *(u32x2*)(yr + 512) = wb_; }
	v_cvt_i32_f32_e32 v51, v51
	v_fmaak_f32 v65, v64, v65, 0x3c0887f9
	v_fmaak_f32 v65, v64, v65, 0x3d2aaa81
	v_fmaak_f32 v65, v64, v65, 0x3e2aaaab
	v_fma_f32 v65, v64, v65, 0.5
	v_ldexp_f32 v51, 1.0, v51
	v_mul_f32_e32 v65, v64, v65
	v_cndmask_b32_e32 v51, v51, v195, vcc
	v_fmac_f32_e32 v64, v64, v65
	v_add_f32_e32 v65, -1.0, v51
	v_fmac_f32_e32 v65, v51, v64
	v_add_f32_e32 v51, v65, v65
	v_cndmask_b32_e32 v51, v65, v51, vcc
	v_max_f32_e64 v51, -v51, 0
	v_cmp_gt_f32_e32 vcc, s19, v51
	v_mul_f32_e32 v64, 0x4f800000, v51
	v_cvt_pk_bf16_f32 v56, v52, v53
	v_mul_f32_e32 v50, 0x3fb8aa3b, v60
	v_cndmask_b32_e32 v51, v51, v64, vcc
	v_sqrt_f32_e32 v64, v51
	v_exp_f32_e32 v50, v50
	v_add_u32_e32 v65, -1, v64
	v_fma_f32 v66, -v65, v64, v51
	v_cmp_ge_f32_e64 s[36:37], 0, v66
	v_add_u32_e32 v66, 1, v64
	s_nop 0
	v_cndmask_b32_e64 v65, v64, v65, s[36:37]
	v_fma_f32 v64, -v66, v64, v51
	v_cmp_lt_f32_e64 s[36:37], 0, v64
	s_nop 1
	v_cndmask_b32_e64 v64, v65, v66, s[36:37]
	v_mul_f32_e32 v65, 0x37800000, v64
	v_cndmask_b32_e32 v64, v64, v65, vcc
	v_cmp_class_f32_e32 vcc, v51, v178
	s_nop 1
	v_cndmask_b32_e32 v51, v64, v51, vcc
	v_mul_f32_e32 v64, 0x3fb8aa3b, v63
	v_rndne_f32_e32 v64, v64
	v_fmamk_f32 v65, v64, 0xbf317218, v63
	v_fmac_f32_e32 v65, 0x3102e308, v64
	v_fmamk_f32 v66, v65, 0x395133b1, v177
	v_cmp_eq_f32_e32 vcc, s2, v64
	v_cvt_i32_f32_e32 v64, v64
	v_fmaak_f32 v66, v65, v66, 0x3c0887f9
	v_fmaak_f32 v66, v65, v66, 0x3d2aaa81
	v_fmaak_f32 v66, v65, v66, 0x3e2aaaab
	v_fma_f32 v66, v65, v66, 0.5
	v_ldexp_f32 v64, 1.0, v64
	v_mul_f32_e32 v66, v65, v66
	v_cndmask_b32_e32 v64, v64, v195, vcc
	v_fmac_f32_e32 v65, v65, v66
	v_add_f32_e32 v66, -1.0, v64
	v_fmac_f32_e32 v66, v64, v65
	v_add_f32_e32 v64, v66, v66
	v_cndmask_b32_e32 v64, v66, v64, vcc
	v_max_f32_e64 v64, -v64, 0
	v_cmp_gt_f32_e32 vcc, s19, v64
	v_mul_f32_e32 v65, 0x4f800000, v64
	s_nop 0
	v_cndmask_b32_e32 v64, v64, v65, vcc
	v_sqrt_f32_e32 v65, v64
	s_nop 0
	v_add_u32_e32 v66, -1, v65
	v_fma_f32 v67, -v66, v65, v64
	v_cmp_ge_f32_e64 s[36:37], 0, v67
	v_add_u32_e32 v67, 1, v65
	s_nop 0
	v_cndmask_b32_e64 v66, v65, v66, s[36:37]
	v_fma_f32 v65, -v67, v65, v64
	v_cmp_lt_f32_e64 s[36:37], 0, v65
	s_nop 1
	v_cndmask_b32_e64 v65, v66, v67, s[36:37]
	v_mul_f32_e32 v66, 0x37800000, v65
	v_cndmask_b32_e32 v65, v65, v66, vcc
	v_cmp_class_f32_e32 vcc, v64, v178
	s_nop 1
	v_cndmask_b32_e32 v64, v65, v64, vcc
	v_cmp_nlt_f32_e32 vcc, s86, v62
	s_nop 1
	v_cndmask_b32_e32 v51, 0, v51, vcc
	v_cmp_nlt_f32_e32 vcc, s86, v63
	s_nop 1
	v_cndmask_b32_e32 v64, 0, v64, vcc
	v_cmp_ngt_f32_e32 vcc, s56, v63
	s_nop 1
	v_cndmask_b32_e32 v63, 1.0, v64, vcc
	v_cmp_ngt_f32_e32 vcc, s56, v62
	s_nop 1
	v_cndmask_b32_e32 v62, 1.0, v51, vcc
	v_pk_mul_f32 v[54:55], v[54:55], v[62:63]
	v_mul_f32_e32 v51, 0x3fb8aa3b, v61
	v_pk_mul_f32 v[54:55], v[54:55], v[58:59]
	v_exp_f32_e32 v51, v51
	v_cvt_pk_bf16_f32 v57, v54, v55
	global_store_dwordx2 v[80:81], v[56:57], off offset:1216
	v_lshl_add_u64 v[56:57], s[26:27], 0, v[70:71]
	v_lshl_add_u64 v[74:75], v[56:57], 0, v[68:69]
	global_load_dwordx4 v[118:121], v[74:75], off
	global_load_dwordx4 v[122:125], v[74:75], off offset:64
	v_lshl_add_u64 v[56:57], s[24:25], 0, v[70:71]
	v_lshl_add_u64 v[88:89], v[56:57], 0, v[68:69]
	global_load_dwordx4 v[126:129], v[88:89], off
	ds_read_b128 v[56:59], v87
	global_load_dwordx4 v[88:91], v[88:89], off offset:64
	s_waitcnt vmcnt(3) lgkmcnt(0)
	v_mfma_f32_16x16x32_bf16 v[60:63], v[118:121], v[56:59], 0
	s_waitcnt vmcnt(1)
	v_mfma_f32_16x16x32_bf16 v[56:59], v[126:129], v[56:59], 0
	ds_read_b128 v[64:67], v87 offset:64
	global_load_dwordx4 v[72:75], v[72:73], off offset:448
	s_nop 0
	s_waitcnt vmcnt(2) lgkmcnt(0)
	v_mfma_f32_16x16x32_bf16 v[60:63], v[122:125], v[64:67], v[60:63]
	s_waitcnt vmcnt(1)
	v_mfma_f32_16x16x32_bf16 v[56:59], v[88:91], v[64:67], v[56:59]
	s_nop 0
	global_load_dwordx4 v[64:67], v[84:85], off offset:448
	global_load_dwordx4 v[68:71], v[82:83], off offset:448
	ds_read_b64 v[82:83], v79
	s_waitcnt lgkmcnt(0)
	v_lshlrev_b32_e32 v84, 16, v82
	v_and_b32_e32 v85, 0xffff0000, v82
	s_waitcnt vmcnt(2)
	v_add_f32_e32 v60, v60, v72
	s_waitcnt vmcnt(1)
	v_add_f32_e32 v56, v56, v64
	v_mul_f32_e32 v60, 0xbfb8aa3b, v60
	v_mul_f32_e32 v56, 0xbfb8aa3b, v56
	v_exp_f32_e32 v60, v60
	v_exp_f32_e32 v56, v56
	v_add_f32_e32 v62, v62, v74
	v_add_f32_e32 v58, v58, v66
	v_add_f32_e32 v60, 1.0, v60
	v_add_f32_e32 v56, 1.0, v56
	v_rcp_f32_e32 v72, v60
	v_rcp_f32_e32 v60, v56
	v_add_f32_e32 v56, v61, v73
	v_mul_f32_e32 v56, 0xbfb8aa3b, v56
	v_exp_f32_e32 v56, v56
	v_mul_f32_e32 v62, 0xbfb8aa3b, v62
	v_mul_f32_e32 v58, 0xbfb8aa3b, v58
	v_exp_f32_e32 v62, v62
	v_add_f32_e32 v56, 1.0, v56
	v_rcp_f32_e32 v73, v56
	v_add_f32_e32 v56, v57, v65
	v_mul_f32_e32 v56, 0xbfb8aa3b, v56
	v_exp_f32_e32 v56, v56
	s_waitcnt vmcnt(0)
; #define LAS __attribute__((address_space(3)))
; __device__ __forceinline__ unsigned pk2(float lo, float hi) { return pg8::cvt_pk_bf16(lo, hi); }
; __device__ __forceinline__ float sigmoidf_(float x) { return __builtin_amdgcn_rcpf(1.0f + __expf(-x)); }
; template <bool FULL> __device__ __forceinline__ void lru_tile(const Args& a, int l, int tile, LAS unsigned char* lds, int tid, int lane, int wave) {
;     ...
;             const int c0 = e0 + 4 * fq;
;             const f32x4 ba = *(const f32x4*)(a.in[22] + (size_t)l * 256 + c0), bx = *(const f32x4*)(a.in[24] + (size_t)l * 256 + c0), c8v = *(const f32x4*)(c8t + c0);
;             const u32x2 xr = *(const LAS u32x2*)(lds + OFF_XC + ((cb * 16 + fr) * 264 + c0) * 2);
;             float lav[4];
;             const float xcv[4] = {__uint_as_float(xr.x << 16), __uint_as_float(xr.x & 0xffff0000u), __uint_as_float(xr.y << 16), __uint_as_float(xr.y & 0xffff0000u)};
; #pragma unroll
;             for (int r = 0; r < 4; ++r) {
;                 const float rg = sigmoidf_(ra[r] + ba[r]), ig = sigmoidf_(ia[r] + bx[r]);
;                 const float la = c8v[r] * rg; const float av_ = __expf(la); const float m2 = -expm1f(2.0f * la);
;                 av[et][r] = av_; bv[et][r] = sqrtf(fmaxf(m2, 0.f)) * ig * xcv[r]; lav[r] = la;
;             }
;             {
;               bf16* yr = Y + (size_t)(t0 + cb * 16 + fr) * DM + c0;
;               u32x2 wl_; wl_.x = pk2(lav[0], lav[1]); wl_.y = pk2(lav[2], lav[3]); *(u32x2*)(yr + 768) = wl_;
;               u32x2 wb_; wb_.x = pk2(bv[et][0], bv[et][1]); wb_.y = pk2(bv[et][2], bv[et][3]); *(u32x2*)(yr + 512) = wb_; }
	v_pk_mul_f32 v[64:65], v[68:69], v[72:73]
	v_exp_f32_e32 v58, v58
	v_pk_add_f32 v[68:69], v[64:65], v[64:65]
	v_add_f32_e32 v56, 1.0, v56
	v_mul_f32_e32 v57, 0x3fb8aa3b, v68
	v_rndne_f32_e32 v57, v57
	v_fmamk_f32 v72, v57, 0xbf317218, v68
	v_fmac_f32_e32 v72, 0x3102e308, v57
	v_fmamk_f32 v73, v72, 0x395133b1, v177
	v_cmp_eq_f32_e32 vcc, s2, v57
	v_cvt_i32_f32_e32 v57, v57
	v_fmaak_f32 v73, v72, v73, 0x3c0887f9
	v_fmaak_f32 v73, v72, v73, 0x3d2aaa81
	v_fmaak_f32 v73, v72, v73, 0x3e2aaaab
	v_fma_f32 v73, v72, v73, 0.5
	v_ldexp_f32 v57, 1.0, v57
	v_mul_f32_e32 v73, v72, v73
	v_cndmask_b32_e32 v57, v57, v195, vcc
	v_fmac_f32_e32 v72, v72, v73
	v_add_f32_e32 v73, -1.0, v57
	v_fmac_f32_e32 v73, v57, v72
	v_add_f32_e32 v57, v73, v73
	v_cndmask_b32_e32 v57, v73, v57, vcc
	v_max_f32_e64 v57, -v57, 0
	v_cmp_gt_f32_e32 vcc, s19, v57
	v_mul_f32_e32 v72, 0x4f800000, v57
	v_rcp_f32_e32 v61, v56
	v_cndmask_b32_e32 v57, v57, v72, vcc
	v_sqrt_f32_e32 v72, v57
	v_add_f32_e32 v62, 1.0, v62
	v_add_f32_e32 v58, 1.0, v58
	v_mul_f32_e32 v56, 0x3fb8aa3b, v64
	v_add_u32_e32 v73, -1, v72
	v_fma_f32 v79, -v73, v72, v57
	v_cmp_ge_f32_e64 s[36:37], 0, v79
	v_add_u32_e32 v79, 1, v72
	v_cvt_pk_bf16_f32 v64, v64, v65
	v_lshlrev_b32_e32 v66, 16, v83
	v_cndmask_b32_e64 v73, v72, v73, s[36:37]
	v_fma_f32 v72, -v79, v72, v57
	v_cmp_lt_f32_e64 s[36:37], 0, v72
	v_exp_f32_e32 v56, v56
	s_nop 0
	v_cndmask_b32_e64 v72, v73, v79, s[36:37]
	v_mul_f32_e32 v73, 0x37800000, v72
	v_cndmask_b32_e32 v72, v72, v73, vcc
	v_cmp_class_f32_e32 vcc, v57, v178
	s_nop 1
	v_cndmask_b32_e32 v57, v72, v57, vcc
	v_mul_f32_e32 v72, 0x3fb8aa3b, v69
	v_rndne_f32_e32 v72, v72
	v_fmamk_f32 v73, v72, 0xbf317218, v69
	v_fmac_f32_e32 v73, 0x3102e308, v72
	v_fmamk_f32 v79, v73, 0x395133b1, v177
	v_cmp_eq_f32_e32 vcc, s2, v72
	v_cvt_i32_f32_e32 v72, v72
	v_fmaak_f32 v79, v73, v79, 0x3c0887f9
	v_fmaak_f32 v79, v73, v79, 0x3d2aaa81
	v_fmaak_f32 v79, v73, v79, 0x3e2aaaab
	v_fma_f32 v79, v73, v79, 0.5
	v_ldexp_f32 v72, 1.0, v72
	v_mul_f32_e32 v79, v73, v79
	v_cndmask_b32_e32 v72, v72, v195, vcc
	v_fmac_f32_e32 v73, v73, v79
	v_add_f32_e32 v79, -1.0, v72
	v_fmac_f32_e32 v79, v72, v73
	v_add_f32_e32 v72, v79, v79
	v_cndmask_b32_e32 v72, v79, v72, vcc
	v_max_f32_e64 v72, -v72, 0
	v_cmp_gt_f32_e32 vcc, s19, v72
	v_mul_f32_e32 v73, 0x4f800000, v72
	s_nop 0
	v_cndmask_b32_e32 v72, v72, v73, vcc
	v_sqrt_f32_e32 v73, v72
	s_nop 0
	v_add_u32_e32 v79, -1, v73
	v_fma_f32 v82, -v79, v73, v72
	v_cmp_ge_f32_e64 s[36:37], 0, v82
	v_add_u32_e32 v82, 1, v73
	s_nop 0
	v_cndmask_b32_e64 v79, v73, v79, s[36:37]
	v_fma_f32 v73, -v82, v73, v72
	v_cmp_lt_f32_e64 s[36:37], 0, v73
	s_nop 1
	v_cndmask_b32_e64 v73, v79, v82, s[36:37]
	v_mul_f32_e32 v79, 0x37800000, v73
	v_cndmask_b32_e32 v73, v73, v79, vcc
	v_cmp_class_f32_e32 vcc, v72, v178
	s_nop 1
	v_cndmask_b32_e32 v72, v73, v72, vcc
	v_cmp_nlt_f32_e32 vcc, s86, v68
	s_nop 1
	v_cndmask_b32_e32 v57, 0, v57, vcc
	v_cmp_nlt_f32_e32 vcc, s86, v69
	s_nop 1
	v_cndmask_b32_e32 v72, 0, v72, vcc
	v_cmp_ngt_f32_e32 vcc, s56, v69
	s_nop 1
	v_cndmask_b32_e32 v69, 1.0, v72, vcc
	v_cmp_ngt_f32_e32 vcc, s56, v68
	s_nop 1
	v_cndmask_b32_e32 v68, 1.0, v57, vcc
	v_pk_mul_f32 v[60:61], v[60:61], v[68:69]
	v_rcp_f32_e32 v68, v62
	v_rcp_f32_e32 v62, v58
	v_add_f32_e32 v58, v63, v75
	v_mul_f32_e32 v58, 0xbfb8aa3b, v58
	v_exp_f32_e32 v58, v58
	v_pk_mul_f32 v[60:61], v[60:61], v[84:85]
	v_mul_f32_e32 v57, 0x3fb8aa3b, v65
	v_exp_f32_e32 v57, v57
	v_add_f32_e32 v58, 1.0, v58
	v_rcp_f32_e32 v69, v58
	v_add_f32_e32 v58, v59, v67
	v_mul_f32_e32 v58, 0xbfb8aa3b, v58
	v_exp_f32_e32 v58, v58
	v_pk_mul_f32 v[68:69], v[70:71], v[68:69]
	v_and_b32_e32 v67, 0xffff0000, v83
	v_pk_add_f32 v[70:71], v[68:69], v[68:69]
	v_add_f32_e32 v58, 1.0, v58
	v_mul_f32_e32 v59, 0x3fb8aa3b, v70
	v_rndne_f32_e32 v59, v59
	v_fmamk_f32 v72, v59, 0xbf317218, v70
	v_fmac_f32_e32 v72, 0x3102e308, v59
	v_fmamk_f32 v73, v72, 0x395133b1, v177
	v_cmp_eq_f32_e32 vcc, s2, v59
	v_cvt_i32_f32_e32 v59, v59
	v_fmaak_f32 v73, v72, v73, 0x3c0887f9
	v_fmaak_f32 v73, v72, v73, 0x3d2aaa81
	v_fmaak_f32 v73, v72, v73, 0x3e2aaaab
	v_fma_f32 v73, v72, v73, 0.5
	v_ldexp_f32 v59, 1.0, v59
	v_mul_f32_e32 v73, v72, v73
	v_cndmask_b32_e32 v59, v59, v195, vcc
	v_fmac_f32_e32 v72, v72, v73
	v_add_f32_e32 v73, -1.0, v59
	v_fmac_f32_e32 v73, v59, v72
	v_add_f32_e32 v59, v73, v73
	v_cndmask_b32_e32 v59, v73, v59, vcc
	v_max_f32_e64 v59, -v59, 0
	v_cmp_gt_f32_e32 vcc, s19, v59
	v_mul_f32_e32 v72, 0x4f800000, v59
	v_rcp_f32_e32 v63, v58
	v_cndmask_b32_e32 v59, v59, v72, vcc
	v_sqrt_f32_e32 v72, v59
	v_cvt_pk_bf16_f32 v65, v68, v69
	global_store_dwordx2 v[80:81], v[64:65], off offset:1760
	v_cvt_pk_bf16_f32 v64, v60, v61
	v_add_u32_e32 v73, -1, v72
	v_fma_f32 v74, -v73, v72, v59
	v_cmp_ge_f32_e64 s[36:37], 0, v74
	v_add_u32_e32 v74, 1, v72
	v_mul_f32_e32 v58, 0x3fb8aa3b, v68
	v_cndmask_b32_e64 v73, v72, v73, s[36:37]
	v_fma_f32 v72, -v74, v72, v59
	v_cmp_lt_f32_e64 s[36:37], 0, v72
	v_exp_f32_e32 v58, v58
	s_nop 0
	v_cndmask_b32_e64 v72, v73, v74, s[36:37]
	v_mul_f32_e32 v73, 0x37800000, v72
	v_cndmask_b32_e32 v72, v72, v73, vcc
	v_cmp_class_f32_e32 vcc, v59, v178
	s_nop 1
	v_cndmask_b32_e32 v59, v72, v59, vcc
	v_mul_f32_e32 v72, 0x3fb8aa3b, v71
	v_rndne_f32_e32 v72, v72
	v_fmamk_f32 v73, v72, 0xbf317218, v71
	v_fmac_f32_e32 v73, 0x3102e308, v72
	v_fmamk_f32 v74, v73, 0x395133b1, v177
	v_cmp_eq_f32_e32 vcc, s2, v72
	v_cvt_i32_f32_e32 v72, v72
	v_fmaak_f32 v74, v73, v74, 0x3c0887f9
	v_fmaak_f32 v74, v73, v74, 0x3d2aaa81
	v_fmaak_f32 v74, v73, v74, 0x3e2aaaab
	v_fma_f32 v74, v73, v74, 0.5
	v_ldexp_f32 v72, 1.0, v72
	v_mul_f32_e32 v74, v73, v74
	v_cndmask_b32_e32 v72, v72, v195, vcc
; #define LAS __attribute__((address_space(3)))
; __device__ __forceinline__ unsigned pk2(float lo, float hi) { return pg8::cvt_pk_bf16(lo, hi); }
; __device__ __forceinline__ float sigmoidf_(float x) { return __builtin_amdgcn_rcpf(1.0f + __expf(-x)); }
; template <bool FULL> __device__ __forceinline__ void lru_tile(const Args& a, int l, int tile, LAS unsigned char* lds, int tid, int lane, int wave) {
;     ...
;             for (int r = 0; r < 4; ++r) {
;                 const float rg = sigmoidf_(ra[r] + ba[r]), ig = sigmoidf_(ia[r] + bx[r]);
;                 const float la = c8v[r] * rg; const float av_ = __expf(la); const float m2 = -expm1f(2.0f * la);
;                 av[et][r] = av_; bv[et][r] = sqrtf(fmaxf(m2, 0.f)) * ig * xcv[r]; lav[r] = la;
;             }
;             {
;               bf16* yr = Y + (size_t)(t0 + cb * 16 + fr) * DM + c0;
;               u32x2 wl_; wl_.x = pk2(lav[0], lav[1]); wl_.y = pk2(lav[2], lav[3]); *(u32x2*)(yr + 768) = wl_;
;               u32x2 wb_; wb_.x = pk2(bv[et][0], bv[et][1]); wb_.y = pk2(bv[et][2], bv[et][3]); *(u32x2*)(yr + 512) = wb_; }
;             if ((et & 3) == 3) asm volatile("" ::: "memory");
;         }
;         __syncthreads();
; #pragma unroll
;         for (int et = 0; et < 8; ++et) { const int c0 = chh * 128 + et * 16 + 4 * fq, t = cb * 16 + fr;
;             *(LAS f32x4*)(lds + OFF_LA + (t * 256 + c0) * 4) = av[et]; *(LAS f32x4*)(lds + OFF_LB + (t * 256 + c0) * 4) = bv[et]; }
;     }
;     }
;     __syncthreads();
;     float* AE = (float*)(a.ws + WS_LRUC); float* HE = AE + 2 * 128 * 256;
;     if (tid < 256) {
;         LAS float* A = (LAS float*)(lds + OFF_LA) + tid; LAS float* B = (LAS float*)(lds + OFF_LB) + tid;
;         float h = FULL ? HE[(size_t)tile * 256 + tid] : 0.f, P = 1.f;
;         for (int tb = 0; tb < 64; tb += 16) {
;             float av_[16], bv_[16];
; #pragma unroll
;             for (int j = 0; j < 16; ++j) { av_[j] = A[(tb + j) * 256]; bv_[j] = B[(tb + j) * 256]; }
; #pragma unroll
;             for (int j = 0; j < 16; ++j) { h = fmaf(av_[j], h, bv_[j]); if (FULL) bv_[j] = h; else P *= av_[j]; }
;             if (FULL) {
; #pragma unroll
;                 for (int j = 0; j < 16; ++j) B[(tb + j) * 256] = bv_[j];
;             }
;         }
;         if (!FULL) { AE[(size_t)tile * 256 + tid] = P; HE[(size_t)tile * 256 + tid] = h; }
	v_fmac_f32_e32 v73, v73, v74
	v_add_f32_e32 v74, -1.0, v72
	v_fmac_f32_e32 v74, v72, v73
	v_add_f32_e32 v72, v74, v74
	v_cndmask_b32_e32 v72, v74, v72, vcc
	v_max_f32_e64 v72, -v72, 0
	v_cmp_gt_f32_e32 vcc, s19, v72
	v_mul_f32_e32 v73, 0x4f800000, v72
	s_nop 0
	v_cndmask_b32_e32 v72, v72, v73, vcc
	v_sqrt_f32_e32 v73, v72
	s_nop 0
	v_add_u32_e32 v74, -1, v73
	v_fma_f32 v75, -v74, v73, v72
	v_cmp_ge_f32_e64 s[36:37], 0, v75
	v_add_u32_e32 v75, 1, v73
	s_nop 0
	v_cndmask_b32_e64 v74, v73, v74, s[36:37]
	v_fma_f32 v73, -v75, v73, v72
	v_cmp_lt_f32_e64 s[36:37], 0, v73
	s_nop 1
	v_cndmask_b32_e64 v73, v74, v75, s[36:37]
	v_mul_f32_e32 v74, 0x37800000, v73
	v_cndmask_b32_e32 v73, v73, v74, vcc
	v_cmp_class_f32_e32 vcc, v72, v178
	s_nop 1
	v_cndmask_b32_e32 v72, v73, v72, vcc
	v_cmp_nlt_f32_e32 vcc, s86, v70
	s_nop 1
	v_cndmask_b32_e32 v59, 0, v59, vcc
	v_cmp_nlt_f32_e32 vcc, s86, v71
	s_nop 1
	v_cndmask_b32_e32 v72, 0, v72, vcc
	v_cmp_ngt_f32_e32 vcc, s56, v71
	s_nop 1
	v_cndmask_b32_e32 v71, 1.0, v72, vcc
	v_cmp_ngt_f32_e32 vcc, s56, v70
	s_nop 1
	v_cndmask_b32_e32 v70, 1.0, v59, vcc
	v_pk_mul_f32 v[62:63], v[62:63], v[70:71]
	v_mul_f32_e32 v59, 0x3fb8aa3b, v69
	v_pk_mul_f32 v[62:63], v[62:63], v[66:67]
	v_exp_f32_e32 v59, v59
	v_cvt_pk_bf16_f32 v65, v62, v63
	global_store_dwordx2 v[80:81], v[64:65], off offset:1248
	v_lshl_or_b32 v64, v77, 10, v78
	v_add_u32_e32 v64, s1, v64
	v_add_u32_e32 v65, 0, v64
	s_barrier
	ds_write_b128 v65, v[0:3]
	v_add_u32_e32 v0, s0, v64
	s_movk_i32 s0, 0x100
	v_cmp_gt_i32_e32 vcc, s0, v76
	ds_write_b128 v0, v[4:7]
	ds_write_b128 v65, v[8:11] offset:64
	ds_write_b128 v0, v[12:15] offset:64
	ds_write_b128 v65, v[16:19] offset:128
	ds_write_b128 v0, v[20:23] offset:128
	ds_write_b128 v65, v[24:27] offset:192
	ds_write_b128 v0, v[28:31] offset:192
	ds_write_b128 v65, v[32:35] offset:256
	ds_write_b128 v0, v[36:39] offset:256
	ds_write_b128 v65, v[40:43] offset:320
	ds_write_b128 v0, v[44:47] offset:320
	ds_write_b128 v65, v[48:51] offset:384
	ds_write_b128 v0, v[52:55] offset:384
	ds_write_b128 v65, v[56:59] offset:448
	ds_write_b128 v0, v[60:63] offset:448
	s_waitcnt lgkmcnt(0)
	s_barrier
	s_and_saveexec_b64 s[0:1], vcc
	s_cbranch_execz .LBB0_1256
	v_lshl_add_u32 v34, v76, 2, 0
	v_add_u32_e32 v35, 0x10000, v34
	ds_read2st64_b32 v[0:1], v34 offset1:4
	ds_read2st64_b32 v[2:3], v35 offset1:4
	ds_read2st64_b32 v[4:5], v34 offset0:8 offset1:12
	ds_read2st64_b32 v[6:7], v35 offset0:8 offset1:12
	ds_read2st64_b32 v[8:9], v34 offset0:16 offset1:20
	ds_read2st64_b32 v[10:11], v35 offset0:16 offset1:20
	ds_read2st64_b32 v[12:13], v34 offset0:24 offset1:28
	ds_read2st64_b32 v[14:15], v35 offset0:24 offset1:28
	ds_read2st64_b32 v[16:17], v34 offset0:32 offset1:36
	ds_read2st64_b32 v[18:19], v35 offset0:32 offset1:36
	ds_read2st64_b32 v[20:21], v34 offset0:40 offset1:44
	ds_read2st64_b32 v[22:23], v35 offset0:40 offset1:44
	ds_read2st64_b32 v[24:25], v34 offset0:48 offset1:52
	ds_read2st64_b32 v[26:27], v35 offset0:48 offset1:52
	ds_read2st64_b32 v[28:29], v34 offset0:56 offset1:60
	ds_read2st64_b32 v[30:31], v35 offset0:56 offset1:60
	s_waitcnt lgkmcnt(14)
	v_fma_f32 v2, 0, v0, v2
	v_fmac_f32_e32 v3, v1, v2
	v_mul_f32_e32 v0, v0, v1
	s_waitcnt lgkmcnt(12)
	v_fma_f32 v1, v4, v3, v6
	v_mul_f32_e32 v0, v0, v4
	v_fmac_f32_e32 v7, v5, v1
	v_mul_f32_e32 v0, v0, v5
	s_waitcnt lgkmcnt(10)
	v_fma_f32 v1, v8, v7, v10
	v_mul_f32_e32 v0, v0, v8
	v_fmac_f32_e32 v11, v9, v1
	v_mul_f32_e32 v0, v0, v9
	s_waitcnt lgkmcnt(8)
	v_fma_f32 v1, v12, v11, v14
	v_mul_f32_e32 v0, v0, v12
	v_fmac_f32_e32 v15, v13, v1
	v_mul_f32_e32 v0, v0, v13
	s_waitcnt lgkmcnt(6)
	v_fma_f32 v1, v16, v15, v18
	v_mul_f32_e32 v0, v0, v16
	v_fmac_f32_e32 v19, v17, v1
	v_mul_f32_e32 v0, v0, v17
	s_waitcnt lgkmcnt(4)
	v_fma_f32 v1, v20, v19, v22
	v_mul_f32_e32 v0, v0, v20
	v_fmac_f32_e32 v23, v21, v1
	v_mul_f32_e32 v0, v0, v21
	s_waitcnt lgkmcnt(2)
	v_fma_f32 v1, v24, v23, v26
	v_mul_f32_e32 v0, v0, v24
	v_fmac_f32_e32 v27, v25, v1
	v_mul_f32_e32 v0, v0, v25
	s_waitcnt lgkmcnt(0)
	v_fma_f32 v1, v28, v27, v30
	v_mul_f32_e32 v0, v0, v28
	v_fmac_f32_e32 v31, v29, v1
	v_mul_f32_e32 v30, v0, v29
	ds_read2st64_b32 v[0:1], v34 offset0:64 offset1:68
	ds_read2st64_b32 v[2:3], v35 offset0:64 offset1:68
	ds_read2st64_b32 v[4:5], v34 offset0:72 offset1:76
	ds_read2st64_b32 v[6:7], v35 offset0:72 offset1:76
	ds_read2st64_b32 v[8:9], v34 offset0:80 offset1:84
	ds_read2st64_b32 v[10:11], v35 offset0:80 offset1:84
	ds_read2st64_b32 v[12:13], v34 offset0:88 offset1:92
	ds_read2st64_b32 v[14:15], v35 offset0:88 offset1:92
	ds_read2st64_b32 v[16:17], v34 offset0:96 offset1:100
	ds_read2st64_b32 v[18:19], v35 offset0:96 offset1:100
	ds_read2st64_b32 v[20:21], v34 offset0:104 offset1:108
	ds_read2st64_b32 v[22:23], v35 offset0:104 offset1:108
	ds_read2st64_b32 v[24:25], v34 offset0:112 offset1:116
	ds_read2st64_b32 v[26:27], v35 offset0:112 offset1:116
	ds_read2st64_b32 v[28:29], v34 offset0:120 offset1:124
	ds_read2st64_b32 v[32:33], v35 offset0:120 offset1:124
	s_waitcnt lgkmcnt(14)
	v_fma_f32 v2, v0, v31, v2
	v_mul_f32_e32 v0, v30, v0
	v_fmac_f32_e32 v3, v1, v2
	v_mul_f32_e32 v0, v0, v1
	s_waitcnt lgkmcnt(12)
; #define LAS __attribute__((address_space(3)))
; template <bool FULL> __device__ __forceinline__ void lru_tile(const Args& a, int l, int tile, LAS unsigned char* lds, int tid, int lane, int wave) {
;     ...
;     if (tid < 256) {
;         LAS float* A = (LAS float*)(lds + OFF_LA) + tid; LAS float* B = (LAS float*)(lds + OFF_LB) + tid;
;         float h = FULL ? HE[(size_t)tile * 256 + tid] : 0.f, P = 1.f;
;         for (int tb = 0; tb < 64; tb += 16) {
;             float av_[16], bv_[16];
; #pragma unroll
;             for (int j = 0; j < 16; ++j) { av_[j] = A[(tb + j) * 256]; bv_[j] = B[(tb + j) * 256]; }
; #pragma unroll
;             for (int j = 0; j < 16; ++j) { h = fmaf(av_[j], h, bv_[j]); if (FULL) bv_[j] = h; else P *= av_[j]; }
;             if (FULL) {
; #pragma unroll
;                 for (int j = 0; j < 16; ++j) B[(tb + j) * 256] = bv_[j];
;             }
;         }
;         if (!FULL) { AE[(size_t)tile * 256 + tid] = P; HE[(size_t)tile * 256 + tid] = h; }
	v_fma_f32 v1, v4, v3, v6
	v_mul_f32_e32 v0, v0, v4
	v_fmac_f32_e32 v7, v5, v1
	v_mul_f32_e32 v0, v0, v5
	s_waitcnt lgkmcnt(10)
	v_fma_f32 v1, v8, v7, v10
	v_mul_f32_e32 v0, v0, v8
	v_fmac_f32_e32 v11, v9, v1
	v_mul_f32_e32 v0, v0, v9
	s_waitcnt lgkmcnt(8)
	v_fma_f32 v1, v12, v11, v14
	v_mul_f32_e32 v0, v0, v12
	v_fmac_f32_e32 v15, v13, v1
	v_mul_f32_e32 v0, v0, v13
	s_waitcnt lgkmcnt(6)
	v_fma_f32 v1, v16, v15, v18
	v_mul_f32_e32 v0, v0, v16
	v_fmac_f32_e32 v19, v17, v1
	v_mul_f32_e32 v0, v0, v17
	s_waitcnt lgkmcnt(4)
	v_fma_f32 v1, v20, v19, v22
	v_mul_f32_e32 v0, v0, v20
	v_fmac_f32_e32 v23, v21, v1
	v_mul_f32_e32 v0, v0, v21
	s_waitcnt lgkmcnt(2)
	v_fma_f32 v1, v24, v23, v26
	v_mul_f32_e32 v0, v0, v24
	v_fmac_f32_e32 v27, v25, v1
	v_mul_f32_e32 v0, v0, v25
	s_waitcnt lgkmcnt(0)
	v_fma_f32 v1, v28, v27, v32
	v_mul_f32_e32 v0, v0, v28
	v_fmac_f32_e32 v33, v29, v1
	v_mul_f32_e32 v32, v0, v29
	ds_read2st64_b32 v[0:1], v34 offset0:128 offset1:132
	ds_read2st64_b32 v[2:3], v35 offset0:128 offset1:132
	ds_read2st64_b32 v[4:5], v34 offset0:136 offset1:140
	ds_read2st64_b32 v[6:7], v35 offset0:136 offset1:140
	ds_read2st64_b32 v[8:9], v34 offset0:144 offset1:148
	ds_read2st64_b32 v[10:11], v35 offset0:144 offset1:148
	ds_read2st64_b32 v[12:13], v34 offset0:152 offset1:156
	ds_read2st64_b32 v[14:15], v35 offset0:152 offset1:156
	ds_read2st64_b32 v[16:17], v34 offset0:160 offset1:164
	ds_read2st64_b32 v[18:19], v35 offset0:160 offset1:164
	ds_read2st64_b32 v[20:21], v34 offset0:168 offset1:172
	ds_read2st64_b32 v[22:23], v35 offset0:168 offset1:172
	ds_read2st64_b32 v[24:25], v34 offset0:176 offset1:180
	ds_read2st64_b32 v[26:27], v35 offset0:176 offset1:180
	ds_read2st64_b32 v[28:29], v34 offset0:184 offset1:188
	ds_read2st64_b32 v[30:31], v35 offset0:184 offset1:188
	s_waitcnt lgkmcnt(14)
	v_fma_f32 v2, v0, v33, v2
	v_mul_f32_e32 v0, v32, v0
	v_fmac_f32_e32 v3, v1, v2
	v_mul_f32_e32 v0, v0, v1
	s_waitcnt lgkmcnt(12)
	v_fma_f32 v1, v4, v3, v6
	v_mul_f32_e32 v0, v0, v4
	v_fmac_f32_e32 v7, v5, v1
	v_mul_f32_e32 v0, v0, v5
	s_waitcnt lgkmcnt(10)
	v_fma_f32 v1, v8, v7, v10
	v_mul_f32_e32 v0, v0, v8
	v_fmac_f32_e32 v11, v9, v1
	v_mul_f32_e32 v0, v0, v9
	s_waitcnt lgkmcnt(8)
	v_fma_f32 v1, v12, v11, v14
	v_mul_f32_e32 v0, v0, v12
	v_fmac_f32_e32 v15, v13, v1
	v_mul_f32_e32 v0, v0, v13
	s_waitcnt lgkmcnt(6)
	v_fma_f32 v1, v16, v15, v18
	v_mul_f32_e32 v0, v0, v16
	v_fmac_f32_e32 v19, v17, v1
	v_mul_f32_e32 v0, v0, v17
	s_waitcnt lgkmcnt(4)
	v_fma_f32 v1, v20, v19, v22
	v_mul_f32_e32 v0, v0, v20
	v_fmac_f32_e32 v23, v21, v1
	v_mul_f32_e32 v0, v0, v21
	s_waitcnt lgkmcnt(2)
	v_fma_f32 v1, v24, v23, v26
	v_mul_f32_e32 v0, v0, v24
	v_fmac_f32_e32 v27, v25, v1
	v_mul_f32_e32 v0, v0, v25
	s_waitcnt lgkmcnt(0)
	v_fma_f32 v1, v28, v27, v30
	v_mul_f32_e32 v0, v0, v28
	v_fmac_f32_e32 v31, v29, v1
	v_mul_f32_e32 v30, v0, v29
	ds_read2st64_b32 v[0:1], v34 offset0:192 offset1:196
	ds_read2st64_b32 v[2:3], v35 offset0:192 offset1:196
	ds_read2st64_b32 v[4:5], v34 offset0:200 offset1:204
	ds_read2st64_b32 v[6:7], v35 offset0:200 offset1:204
	ds_read2st64_b32 v[8:9], v34 offset0:208 offset1:212
	ds_read2st64_b32 v[10:11], v35 offset0:208 offset1:212
	ds_read2st64_b32 v[12:13], v34 offset0:216 offset1:220
	ds_read2st64_b32 v[14:15], v35 offset0:216 offset1:220
	ds_read2st64_b32 v[16:17], v34 offset0:224 offset1:228
	ds_read2st64_b32 v[18:19], v35 offset0:224 offset1:228
	ds_read2st64_b32 v[20:21], v34 offset0:232 offset1:236
	ds_read2st64_b32 v[22:23], v35 offset0:232 offset1:236
	ds_read2st64_b32 v[24:25], v34 offset0:240 offset1:244
	ds_read2st64_b32 v[26:27], v35 offset0:240 offset1:244
	ds_read2st64_b32 v[28:29], v34 offset0:248 offset1:252
	ds_read2st64_b32 v[32:33], v35 offset0:248 offset1:252
	s_waitcnt lgkmcnt(14)
	v_fma_f32 v2, v0, v31, v2
	v_mul_f32_e32 v0, v30, v0
	v_fmac_f32_e32 v3, v1, v2
	v_mul_f32_e32 v0, v0, v1
	s_waitcnt lgkmcnt(12)
	v_fma_f32 v1, v4, v3, v6
	v_mul_f32_e32 v0, v0, v4
	v_fmac_f32_e32 v7, v5, v1
	v_mul_f32_e32 v0, v0, v5
	s_waitcnt lgkmcnt(10)
	v_fma_f32 v1, v8, v7, v10
	v_mul_f32_e32 v0, v0, v8
	v_fmac_f32_e32 v11, v9, v1
	v_mul_f32_e32 v0, v0, v9
	s_waitcnt lgkmcnt(8)
	v_fma_f32 v1, v12, v11, v14
	v_mul_f32_e32 v0, v0, v12
	v_fmac_f32_e32 v15, v13, v1
	v_mul_f32_e32 v0, v0, v13
	s_waitcnt lgkmcnt(6)
	v_fma_f32 v1, v16, v15, v18
	v_mul_f32_e32 v0, v0, v16
	v_fmac_f32_e32 v19, v17, v1
	v_mul_f32_e32 v0, v0, v17
	s_waitcnt lgkmcnt(4)
	v_fma_f32 v1, v20, v19, v22
	v_mul_f32_e32 v0, v0, v20
	v_fmac_f32_e32 v23, v21, v1
	v_mul_f32_e32 v0, v0, v21
	s_waitcnt lgkmcnt(2)
	v_fma_f32 v1, v24, v23, v26
	v_mul_f32_e32 v0, v0, v24
	v_fmac_f32_e32 v27, v25, v1
	v_mul_f32_e32 v0, v0, v25
	s_ashr_i32 s39, s38, 31
	s_waitcnt lgkmcnt(0)
	v_fma_f32 v1, v28, v27, v32
	v_mul_f32_e32 v0, v0, v28
	s_lshl_b64 s[4:5], s[38:39], 8
	v_ashrrev_i32_e32 v77, 31, v76
	v_fmac_f32_e32 v33, v29, v1
	v_mul_f32_e32 v4, v0, v29
	v_lshl_add_u64 v[0:1], s[4:5], 0, v[76:77]
	v_readlane_b32 s4, v252, 56
	v_lshlrev_b64 v[0:1], 2, v[0:1]
	v_readlane_b32 s5, v252, 57
	s_nop 1
	v_lshl_add_u64 v[2:3], s[4:5], 0, v[0:1]
	v_readlane_b32 s4, v252, 54
	v_readlane_b32 s5, v252, 55
	global_store_dword v[2:3], v4, off
	s_nop 0
	v_lshl_add_u64 v[0:1], s[4:5], 0, v[0:1]
	global_store_dword v[0:1], v33, off
	s_branch .LBB0_1256
